# plus: bf16 conversion of the layer-1 weights moved out of phase 0 into the idle tail of phase 1 (workgroups >=128 re-enter the prep loop with a virtual block index while the others run the half tiles)
# baseline (speedup 1.0000x reference)
;   DI unsigned* bar() const { return (unsigned*)(ws + OFF_BAR); }
; #define LAS __attribute__((address_space(3)))
; __device__ __forceinline__ unsigned xb_add(unsigned* p, unsigned v) { return __hip_atomic_fetch_add(p, v, __ATOMIC_RELAXED, __HIP_MEMORY_SCOPE_AGENT); }
; __device__ __forceinline__ unsigned xb_xcc_id() { return (unsigned)__builtin_amdgcn_s_getreg((3 << 11) | 20) & 0xFu; }
; __device__ __forceinline__ XcdBarrier xcd_barrier_post(unsigned* bar, volatile LAS unsigned* st) {
;     XcdBarrier b; b.bar = bar; b.x = xb_xcc_id(); b.st = st;
;     if (threadIdx.x == 0) (void)xb_add(&bar[XB_XCNT(b.x)], 1u);
;     return b;
; __global__ void __launch_bounds__(NTH, 2) mega_kernel(Params p) {
;   extern __shared__ __attribute__((aligned(16))) char smem[];
;   cg::grid_group grid = cg::this_grid();
;   __shared__ __attribute__((aligned(16))) unsigned xb_st[4];
;   if (threadIdx.x < 4) xb_st[threadIdx.x] = 0u;
;   __syncthreads();
;   const XcdBarrier xb = xcd_barrier_post(p.bar(), (volatile LAS unsigned*)xb_st);
_Z11mega_kernel6Params:
	s_load_dword s3, s[0:1], 0xd8
	s_load_dwordx4 s[20:23], s[0:1], 0xc0
	s_load_dwordx2 s[96:97], s[0:1], 0xd0
	s_mov_b32 s84, s2
	s_add_u32 s2, s0, 0xd0
	v_and_b32_e32 v206, 0x3ff, v0
	s_waitcnt lgkmcnt(0)
	v_writelane_b32 v252, s3, 0
	s_addc_u32 s3, s1, 0
	s_mov_b32 s101, 0
	s_movk_i32 s99, 0x63f
	v_cmp_gt_u32_e32 vcc, 4, v206
	v_lshlrev_b32_e32 v2, 2, v206
	s_and_saveexec_b64 s[4:5], vcc
	v_mov_b32_e32 v1, 0
	ds_write_b32 v2, v1
	s_or_b64 exec, exec, s[4:5]
	s_waitcnt lgkmcnt(0)
	s_barrier
	s_add_u32 s94, s22, 0x1e6c1000
	s_getreg_b32 s4, hwreg(HW_REG_XCC_ID, 0, 4)
	s_addc_u32 s95, s23, 0
	s_and_b32 s4, s4, 15
	v_writelane_b32 v252, s4, 1
	v_cmp_eq_u32_e64 s[6:7], 0, v206
	s_mov_b64 s[4:5], exec
	s_nop 0
	v_writelane_b32 v252, s6, 2
	s_nop 1
	v_writelane_b32 v252, s7, 3
	s_and_b64 s[6:7], s[4:5], s[6:7]
	s_mov_b64 exec, s[6:7]
	s_cbranch_execz .LBB0_5
	s_mov_b64 s[6:7], exec
	v_mbcnt_lo_u32_b32 v1, s6, 0
	v_mbcnt_hi_u32_b32 v1, s7, v1
	v_cmp_eq_u32_e32 vcc, 0, v1
	s_and_b64 s[8:9], exec, vcc
	s_mov_b64 exec, s[8:9]
	s_cbranch_execz .LBB0_5
	v_readlane_b32 s8, v252, 1
	s_lshl_b32 s8, s8, 8
	s_bcnt1_i32_b64 s6, s[6:7]
	v_mov_b32_e32 v1, s8
	v_mov_b32_e32 v3, s6
	global_atomic_add v1, v3, s[94:95] offset:1024

;   DI bf16_t* wt_in0() const { return (bf16_t*)(ws + OFF_WT_IN0); }
; DI void prep_weights(const Params& p, char* smem) {
;   const int half = threadIdx.x >> 8, tid = threadIdx.x & 255;
;   float* lds = (float*)smem + half * (64 * TP);
;   constexpr int J0 = 34 * 32, J1 = 16 * 32, J3 = 52 * 32, J4 = 12 * 12, J5 = 16 * 8, J6 = 16 * 32;
;   constexpr int TOT = J0 + J1 + J3 + J4 + J5 + J6;
;   for (int t0 = blockIdx.x * 2; t0 < TOT; t0 += gridDim.x * 2) {
;     const int t = t0 + half;
;     TJob j{}; j.valid = t < TOT;
;     int u = t;
;     if (!j.valid) { }
;     else if (u < J0) { const int nt = u / 32, kt = u % 32; j = TJob{p.w_in0, 4352, nt * 128, p.wt_in0(), 2048, nt * 128, kt * 64, nullptr, 128, true}; }
.Lprep_entry:
	s_lshl_b32 s33, s96, 1
	s_add_u32 s8, s22, 0x37c0000
	s_addc_u32 s9, s23, 0
	v_lshlrev_b32_e32 v4, 5, v206
	s_add_u32 s10, s22, 0x35c0000
	v_and_b32_e32 v4, 32, v4
	s_addc_u32 s11, s23, 0
	v_lshrrev_b32_e32 v1, 8, v206
	s_mov_b32 s0, 0x8400
	v_bfe_u32 v54, v206, 1, 7
	v_mul_u32_u24_e32 v7, 0x84, v4
	s_add_u32 s12, s22, 0x3380000
	v_mad_u32_u24 v3, v1, s0, 16
	v_and_b32_e32 v2, 0x7c, v2
	v_lshlrev_b32_e32 v7, 2, v7
	v_lshlrev_b32_e32 v8, 2, v54
	s_addc_u32 s13, s23, 0
	v_lshl_add_u32 v5, v2, 2, v3
	v_add3_u32 v55, v3, v7, v8
	v_add3_u32 v56, v3, v8, v7
	s_add_u32 s14, s22, 0x1980000
	v_lshlrev_b32_e32 v3, 6, v1
	v_bfe_u32 v34, v206, 5, 3
	s_addc_u32 s15, s23, 0
	v_lshl_add_u32 v57, s84, 7, v3
	v_lshlrev_b32_e32 v3, 2, v1
	v_mov_b32_e32 v37, 0
	v_mul_u32_u24_e32 v6, 0x210, v34
	s_add_u32 s16, s22, 0x1100000
	v_lshl_add_u32 v58, s84, 3, v3
	v_lshlrev_b32_e32 v3, 4, v1
	v_cmp_gt_u32_e32 vcc, 64, v2
	s_addc_u32 s17, s23, 0
	v_mov_b32_e32 v35, v37
	s_lshl_b32 s36, s96, 7
	s_lshl_b32 s37, s96, 3
	v_lshl_add_u32 v59, s84, 5, v3
	s_lshl_b32 s38, s96, 5
	s_movk_i32 s39, 0x1940
	v_lshlrev_b32_e32 v36, 2, v2
	v_lshlrev_b32_e32 v38, 1, v4
	v_mov_b32_e32 v60, 6
	v_add_u32_e32 v61, v5, v6
	s_lshl_b32 s40, s84, 1
	s_branch .LBB0_8
.LBB0_7:
	s_or_b64 exec, exec, s[0:1]
	s_add_i32 s40, s40, s33
	v_add_u32_e32 v57, s36, v57
	v_add_u32_e32 v58, s37, v58
	s_cmp_gt_i32 s40, s99
	v_add_u32_e32 v59, s38, v59
	s_cbranch_scc1 .LBB0_72

;   DI bf16_t* wt_g() const { return (bf16_t*)(ws + OFF_WT_G); }
;   DI bf16_t* z() const { return (bf16_t*)(ws + OFF_Z); }
; DI int otid() { int t = threadIdx.x; asm volatile("" : "+v"(t)); return t; }
; DI void prep_weights(const Params& p, char* smem) {
;     ...
;   for (int i = blockIdx.x * NTH + otid(); i < 2048 * 16; i += gridDim.x * NTH) {
;     const int r = i >> 4, d0 = (i & 15) * 8, gi = r >> 8, nl = r & 255, c32 = nl >> 6, which = (nl >> 5) & 1, e = c32 * 32 + (nl & 31);
;     const float* src = (which ? p.ga_w : p.gx_w) + (size_t)gi * 128 * 128 + e;
;     u32x4 o;
;     o.x = pk_bf16(src[(d0 + 0) * 128], src[(d0 + 1) * 128]); o.y = pk_bf16(src[(d0 + 2) * 128], src[(d0 + 3) * 128]);
;     o.z = pk_bf16(src[(d0 + 4) * 128], src[(d0 + 5) * 128]); o.w = pk_bf16(src[(d0 + 6) * 128], src[(d0 + 7) * 128]);
;     *(u32x4*)(p.wt_g() + (size_t)r * 128 + d0) = o;
;   }
.LBB0_72:
	s_cmp_lg_u32 s101, 0
	s_cbranch_scc1 .Lprep2_ret
	s_lshl_b32 s0, s84, 9
	v_mov_b32_e32 v2, v206
	v_writelane_b32 v252, s0, 37
	v_add_u32_e32 v1, s0, v2
	s_mov_b32 s0, 0x8000
	v_cmp_gt_i32_e32 vcc, s0, v1
	s_and_saveexec_b64 s[0:1], vcc
	s_cbranch_execz .LBB0_75
	v_readlane_b32 s36, v252, 4
	s_lshl_b32 s8, s96, 9
	v_readlane_b32 s37, v252, 5
	s_add_u32 s4, s22, 0x1900000
	v_lshlrev_b32_e32 v2, 3, v2
	v_readlane_b32 s38, v252, 6
	v_readlane_b32 s39, v252, 7
	v_readlane_b32 s40, v252, 8
	v_readlane_b32 s41, v252, 9
	v_readlane_b32 s42, v252, 10
	v_readlane_b32 s43, v252, 11
	s_mov_b64 s[12:13], s[36:37]
	s_addc_u32 s5, s23, 0
	v_lshl_add_u32 v4, s84, 12, v2
	s_lshl_b32 s9, s96, 12
	s_mov_b64 s[6:7], 0
	s_movk_i32 s10, 0x60
	v_mov_b32_e32 v5, s13
	v_mov_b32_e32 v6, s81
	v_mov_b32_e32 v7, s12
	v_mov_b32_e32 v8, s80
	v_mov_b32_e32 v3, 0
	s_movk_i32 s11, 0x7fff
	v_readlane_b32 s44, v252, 12
	v_readlane_b32 s45, v252, 13
	v_readlane_b32 s46, v252, 14
	v_readlane_b32 s47, v252, 15
	v_readlane_b32 s48, v252, 16
	v_readlane_b32 s49, v252, 17
	v_readlane_b32 s50, v252, 18
	v_readlane_b32 s51, v252, 19
	s_mov_b64 s[14:15], s[38:39]
	s_mov_b64 s[16:17], s[40:41]
	s_mov_b64 s[18:19], s[42:43]

; DI int otid() { int t = threadIdx.x; asm volatile("" : "+v"(t)); return t; }
; #define H_MMA(F) { _Pragma("unroll") for (int mb = 0; mb < 4; ++mb) acc[mb] = __builtin_amdgcn_mfma_f32_32x32x16_bf16(F[4], F[mb], acc[mb], 0, 0, 0); }
; DI void gemm_half_rowbf16(const bf16_t* __restrict__ A, int lda, const bf16_t* __restrict__ Bt, int ldb, int K, int m0, int n0, char* smem, bf16_t* __restrict__ Out, int ldo) {
;   bf16_t* lds = (bf16_t*)smem;
;   const int tid = otid(), lane = tid & 63, w = __builtin_amdgcn_readfirstlane(tid >> 6), l32 = lane & 31, g = lane >> 5;
;   f32x16 acc[4];
; #pragma unroll
;   for (int b = 0; b < 4; ++b)
; #pragma unroll
;     for (int r = 0; r < 16; ++r) acc[b][r] = 0.f;
;   const int lrow = tid >> 3, kc = tid & 7;
;   const unsigned aoff = (unsigned)(lrow * lda + kc * 8) * 2u, boff = (unsigned)(lrow * ldb + kc * 8) * 2u;
;   const char* ag = (const char*)(A + (size_t)m0 * lda);
;   const char* bg = (const char*)(Bt + (size_t)n0 * ldb);
;   u32x4 ra[2], rb[4];
;     ...
;   const int nk = K / 64;
;   H_LOADA(0, 0); H_LOADA(1, 0); H_LOADB(0, 0); H_LOADB(1, 0); H_LOADB(2, 0); H_LOADB(3, 0);
;   H_STOREA(0, 0); H_STOREA(0, 1); H_STOREB(0, 0); H_STOREB(0, 1); H_STOREB(0, 2); H_STOREB(0, 3);
;   if (nk > 1) { H_LOADA(0, 1); H_LOADA(1, 1); H_LOADB(0, 1); H_LOADB(1, 1); H_LOADB(2, 1); H_LOADB(3, 1); }
;   for (int kt = 0; kt < nk; ++kt) {
;     const int st = kt & 1;
;     __syncthreads();
;     bf16x8 f0[5], f1[5];
;     H_FRAGS(f0, st, 0);
;     H_PART(0, st, kt); H_FRAGS(f1, st, 1); H_MMA(f0); __builtin_amdgcn_sched_barrier(0);
;     H_PART(1, st, kt); H_FRAGS(f0, st, 2); H_MMA(f1); __builtin_amdgcn_sched_barrier(0);
;     H_PART(2, st, kt); H_FRAGS(f1, st, 3); H_MMA(f0); __builtin_amdgcn_sched_barrier(0);
;     H_PART(3, st, kt); H_MMA(f1); __builtin_amdgcn_sched_barrier(0);
;   }
.LBB0_131:
	v_mov_b32_e32 v28, v206
	s_ashr_i32 s31, s30, 31
	s_lshl_b64 s[34:35], s[30:31], 12
	v_lshlrev_b32_e32 v0, 4, v28
	v_readlane_b32 s31, v252, 59
	v_ashrrev_i32_e32 v24, 3, v28
	v_and_b32_e32 v75, 0x70, v0
	s_add_u32 s34, s31, s34
	v_readlane_b32 s31, v252, 60
	v_lshl_or_b32 v66, v24, 12, v75
	s_addc_u32 s35, s31, s35
	v_lshl_add_u64 v[4:5], s[34:35], 0, v[66:67]
	s_mov_b32 s31, 0x40000
	v_add_co_u32_e32 v68, vcc, s31, v4
	global_load_dwordx4 v[0:3], v66, s[34:35]
	s_nop 0
	v_addc_co_u32_e32 v69, vcc, 0, v5, vcc
	v_readlane_b32 vcc_lo, v252, 61
	v_readlane_b32 vcc_hi, v252, 62
	global_load_dwordx4 v[4:7], v66, s[4:5]
	s_movk_i32 s54, 0x90
	v_mul_lo_u32 v76, v24, s54
	v_readfirstlane_b32 s31, v28
	s_ashr_i32 s31, s31, 1
	global_load_dwordx4 v[8:11], v66, vcc
	v_readlane_b32 vcc_lo, v252, 63
	v_readlane_b32 vcc_hi, v251, 0
	v_mov_b32_e32 v29, s31
	v_bfe_u32 v70, v28, 5, 1
	v_bfi_b32 v29, s49, v29, v28
	v_and_b32_e32 v71, 31, v28
	v_lshlrev_b32_e32 v136, 4, v70
	global_load_dwordx4 v[12:15], v66, vcc
	v_readlane_b32 vcc_lo, v251, 1
	v_readlane_b32 vcc_hi, v251, 2
	s_nop 4
	global_load_dwordx4 v[16:19], v66, vcc
	global_load_dwordx4 v[20:23], v[68:69], off
	v_readlane_b32 vcc_lo, v251, 3
	v_readlane_b32 vcc_hi, v251, 4
	v_mul_lo_u32 v137, v29, s54
	v_mul_u32_u24_e32 v138, 0x90, v71
	v_add3_u32 v73, 16, v76, v75
	v_add3_u32 v72, 16, v137, v136
	v_add3_u32 v74, 16, v138, v136
	global_load_dwordx4 v[84:87], v66, vcc
	v_readlane_b32 vcc_lo, v251, 5
	v_readlane_b32 vcc_hi, v251, 6
	v_add3_u32 v77, s33, v76, v75
	v_add3_u32 v78, s42, v76, v75
	s_andn2_b32 s31, s31, 31
	s_nop 1
	global_load_dwordx4 v[88:91], v66, vcc
	v_readlane_b32 vcc_lo, v251, 7
	v_readlane_b32 vcc_hi, v251, 8
	s_nop 4
	global_load_dwordx4 v[80:83], v66, vcc
	v_readlane_b32 vcc_lo, v251, 9
	v_readlane_b32 vcc_hi, v251, 10
	s_nop 4
	global_load_dwordx4 v[24:27], v66, vcc
	global_load_dwordx4 v[92:95], v66, s[34:35] offset:128
	global_load_dwordx4 v[96:99], v[68:69], off offset:128
	s_waitcnt vmcnt(11)
	ds_write_b128 v73, v[0:3]
	s_waitcnt vmcnt(10)
	ds_write_b128 v73, v[4:7] offset:36864
	s_waitcnt vmcnt(9)
	ds_write_b128 v73, v[8:11] offset:46080
	s_waitcnt vmcnt(8)
	ds_write_b128 v73, v[12:15] offset:55296
	s_waitcnt vmcnt(7)
	ds_write_b128 v73, v[16:19] offset:64512
	s_waitcnt vmcnt(6)
	ds_write_b128 v73, v[20:23] offset:9216
	s_waitcnt lgkmcnt(0)
	s_barrier
	ds_read_b128 v[0:3], v72 offset:36864
	ds_read_b128 v[4:7], v74
	ds_read_b128 v[8:11], v74 offset:4608
	global_load_dwordx4 v[100:103], v66, s[4:5] offset:256
	global_load_dwordx4 v[104:107], v66, s[34:35] offset:256
	s_waitcnt lgkmcnt(1)
	v_mfma_f32_32x32x16_bf16 v[48:63], v[0:3], v[4:7], 0
	ds_read_b128 v[4:7], v74 offset:9216
	s_waitcnt lgkmcnt(1)
	v_mfma_f32_32x32x16_bf16 v[32:47], v[0:3], v[8:11], 0
	ds_read_b128 v[8:11], v74 offset:13824
	s_waitcnt vmcnt(4)
	ds_write_b128 v77, v[24:27]
	s_waitcnt vmcnt(3)
	ds_write_b128 v78, v[92:95]
	ds_read_b128 v[92:95], v74 offset:32
	ds_read_b128 v[108:111], v74 offset:4640
	ds_read_b128 v[112:115], v74 offset:9248
	ds_read_b128 v[116:119], v74 offset:13856
	ds_read_b128 v[120:123], v72 offset:36896
	s_waitcnt lgkmcnt(8)
	v_mfma_f32_32x32x16_bf16 v[16:31], v[0:3], v[4:7], 0
	s_waitcnt lgkmcnt(7)
	v_mfma_f32_32x32x16_bf16 v[0:15], v[0:3], v[8:11], 0
	v_readlane_b32 vcc_lo, v251, 11
	v_readlane_b32 vcc_hi, v251, 12
	s_waitcnt lgkmcnt(0)
	v_mfma_f32_32x32x16_bf16 v[48:63], v[120:123], v[92:95], v[48:63]
	v_add_u32_e32 v79, 0x1d400, v73
	ds_write_b128 v79, v[80:83]
	v_add_u32_e32 v80, 0x14400, v73
	s_waitcnt vmcnt(2)
	ds_write_b128 v80, v[96:99]
	global_load_dwordx4 v[92:95], v66, vcc
	v_mfma_f32_32x32x16_bf16 v[32:47], v[120:123], v[108:111], v[32:47]
	global_load_dwordx4 v[108:111], v[68:69], off offset:256
	v_mfma_f32_32x32x16_bf16 v[16:31], v[120:123], v[112:115], v[16:31]
	ds_read_b128 v[96:99], v74 offset:64
	ds_read_b128 v[112:115], v74 offset:4672
	ds_read_b128 v[124:127], v74 offset:9280
	ds_read_b128 v[128:131], v74 offset:13888
	ds_read_b128 v[132:135], v72 offset:36928
	v_mfma_f32_32x32x16_bf16 v[0:15], v[120:123], v[116:119], v[0:15]
	v_readlane_b32 vcc_lo, v251, 13
	v_readlane_b32 vcc_hi, v251, 14
	s_waitcnt lgkmcnt(0)
	v_mfma_f32_32x32x16_bf16 v[48:63], v[132:135], v[96:99], v[48:63]
	v_add_u32_e32 v81, 0x1f800, v73
	ds_write_b128 v81, v[88:91]
	s_nop 0
	global_load_dwordx4 v[96:99], v66, vcc
	v_mfma_f32_32x32x16_bf16 v[32:47], v[132:135], v[112:115], v[32:47]
	v_mfma_f32_32x32x16_bf16 v[16:31], v[132:135], v[124:127], v[16:31]
	ds_read_b128 v[88:91], v74 offset:96
	ds_read_b128 v[112:115], v74 offset:4704
	ds_read_b128 v[116:119], v74 offset:9312
	ds_read_b128 v[120:123], v74 offset:13920
	ds_read_b128 v[124:127], v72 offset:36960
	v_mfma_f32_32x32x16_bf16 v[0:15], v[132:135], v[128:131], v[0:15]
	v_readlane_b32 vcc_lo, v251, 15
	v_readlane_b32 vcc_hi, v251, 16
	s_waitcnt lgkmcnt(0)
	v_mfma_f32_32x32x16_bf16 v[48:63], v[124:127], v[88:91], v[48:63]
	v_add_u32_e32 v82, 0x21c00, v73
	ds_write_b128 v82, v[84:87]
	s_nop 0
	global_load_dwordx4 v[88:91], v66, vcc
	v_mfma_f32_32x32x16_bf16 v[32:47], v[124:127], v[112:115], v[32:47]
	v_mfma_f32_32x32x16_bf16 v[16:31], v[124:127], v[116:119], v[16:31]
	v_mfma_f32_32x32x16_bf16 v[0:15], v[124:127], v[120:123], v[0:15]
	v_add3_u32 v75, s33, v137, v136
	s_waitcnt lgkmcnt(0)
	s_barrier
; #define H_MMA(F) { _Pragma("unroll") for (int mb = 0; mb < 4; ++mb) acc[mb] = __builtin_amdgcn_mfma_f32_32x32x16_bf16(F[4], F[mb], acc[mb], 0, 0, 0); }
; DI void gemm_half_rowbf16(const bf16_t* __restrict__ A, int lda, const bf16_t* __restrict__ Bt, int ldb, int K, int m0, int n0, char* smem, bf16_t* __restrict__ Out, int ldo) {
;     ...
;   for (int kt = 0; kt < nk; ++kt) {
;     const int st = kt & 1;
;     __syncthreads();
;     bf16x8 f0[5], f1[5];
;     H_FRAGS(f0, st, 0);
;     H_PART(0, st, kt); H_FRAGS(f1, st, 1); H_MMA(f0); __builtin_amdgcn_sched_barrier(0);
;     H_PART(1, st, kt); H_FRAGS(f0, st, 2); H_MMA(f1); __builtin_amdgcn_sched_barrier(0);
;     H_PART(2, st, kt); H_FRAGS(f1, st, 3); H_MMA(f0); __builtin_amdgcn_sched_barrier(0);
;     H_PART(3, st, kt); H_MMA(f1); __builtin_amdgcn_sched_barrier(0);
;   }
	ds_read_b128 v[84:87], v75
	v_add3_u32 v76, s42, v138, v136
	ds_read_b128 v[112:115], v76
	ds_read_b128 v[116:119], v76 offset:4608
	s_waitcnt lgkmcnt(1)
	v_mfma_f32_32x32x16_bf16 v[48:63], v[84:87], v[112:115], v[48:63]
	s_waitcnt lgkmcnt(0)
	v_mfma_f32_32x32x16_bf16 v[32:47], v[84:87], v[116:119], v[32:47]
	global_load_dwordx4 v[112:115], v66, s[4:5] offset:384
	global_load_dwordx4 v[116:119], v66, s[34:35] offset:384
	ds_read_b128 v[120:123], v76 offset:9216
	ds_read_b128 v[124:127], v76 offset:13824
	s_waitcnt vmcnt(7)
	ds_write_b128 v73, v[100:103] offset:36864
	s_waitcnt vmcnt(6)
	ds_write_b128 v73, v[104:107]
	s_waitcnt lgkmcnt(3)
	v_mfma_f32_32x32x16_bf16 v[16:31], v[84:87], v[120:123], v[16:31]
	ds_read_b128 v[100:103], v76 offset:32
	ds_read_b128 v[104:107], v76 offset:4640
	ds_read_b128 v[120:123], v76 offset:9248
	ds_read_b128 v[128:131], v76 offset:13856
	ds_read_b128 v[132:135], v75 offset:32
	s_waitcnt lgkmcnt(7)
	v_mfma_f32_32x32x16_bf16 v[0:15], v[84:87], v[124:127], v[0:15]
	v_readlane_b32 vcc_lo, v251, 17
	v_readlane_b32 vcc_hi, v251, 18
	s_waitcnt lgkmcnt(0)
	v_mfma_f32_32x32x16_bf16 v[48:63], v[132:135], v[100:103], v[48:63]
	global_load_dwordx4 v[100:103], v[68:69], off offset:384
	s_nop 1
	global_load_dwordx4 v[84:87], v66, vcc
	s_waitcnt vmcnt(7)
	ds_write_b128 v73, v[92:95] offset:46080
	s_waitcnt vmcnt(6)
	ds_write_b128 v73, v[108:111] offset:9216
	v_mfma_f32_32x32x16_bf16 v[32:47], v[132:135], v[104:107], v[32:47]
	v_mfma_f32_32x32x16_bf16 v[16:31], v[132:135], v[120:123], v[16:31]
	ds_read_b128 v[92:95], v76 offset:64
	ds_read_b128 v[104:107], v76 offset:4672
	ds_read_b128 v[108:111], v76 offset:9280
	ds_read_b128 v[120:123], v76 offset:13888
	ds_read_b128 v[124:127], v75 offset:64
	v_mfma_f32_32x32x16_bf16 v[0:15], v[132:135], v[128:131], v[0:15]
	v_readlane_b32 vcc_lo, v251, 19
	v_readlane_b32 vcc_hi, v251, 20
	s_waitcnt lgkmcnt(0)
	v_mfma_f32_32x32x16_bf16 v[48:63], v[124:127], v[92:95], v[48:63]
	s_waitcnt vmcnt(5)
	ds_write_b128 v73, v[96:99] offset:55296
	s_nop 0
	global_load_dwordx4 v[92:95], v66, vcc
	v_mfma_f32_32x32x16_bf16 v[32:47], v[124:127], v[104:107], v[32:47]
	v_mfma_f32_32x32x16_bf16 v[16:31], v[124:127], v[108:111], v[16:31]
	ds_read_b128 v[96:99], v76 offset:96
	ds_read_b128 v[104:107], v76 offset:4704
	ds_read_b128 v[108:111], v76 offset:9312
	ds_read_b128 v[128:131], v76 offset:13920
	ds_read_b128 v[132:135], v75 offset:96
	v_mfma_f32_32x32x16_bf16 v[0:15], v[124:127], v[120:123], v[0:15]
	v_readlane_b32 vcc_lo, v251, 21
	v_readlane_b32 vcc_hi, v251, 22
	s_waitcnt lgkmcnt(0)
	v_mfma_f32_32x32x16_bf16 v[48:63], v[132:135], v[96:99], v[48:63]
	s_waitcnt vmcnt(5)
	ds_write_b128 v73, v[88:91] offset:64512
	s_nop 0
	global_load_dwordx4 v[96:99], v66, vcc
	v_mfma_f32_32x32x16_bf16 v[32:47], v[132:135], v[104:107], v[32:47]
	v_mfma_f32_32x32x16_bf16 v[16:31], v[132:135], v[108:111], v[16:31]
	v_mfma_f32_32x32x16_bf16 v[0:15], v[132:135], v[128:131], v[0:15]
	s_waitcnt lgkmcnt(0)
	s_barrier
	ds_read_b128 v[88:91], v72 offset:36864
	ds_read_b128 v[104:107], v74
	ds_read_b128 v[108:111], v74 offset:4608
	s_waitcnt lgkmcnt(1)
	v_mfma_f32_32x32x16_bf16 v[48:63], v[88:91], v[104:107], v[48:63]
	s_waitcnt lgkmcnt(0)
	v_mfma_f32_32x32x16_bf16 v[32:47], v[88:91], v[108:111], v[32:47]
	global_load_dwordx4 v[104:107], v66, s[4:5] offset:512
	global_load_dwordx4 v[108:111], v66, s[34:35] offset:512
	ds_read_b128 v[120:123], v74 offset:9216
	ds_read_b128 v[124:127], v74 offset:13824
	s_waitcnt vmcnt(7)
	ds_write_b128 v77, v[112:115]
	s_waitcnt vmcnt(6)
	ds_write_b128 v78, v[116:119]
	s_waitcnt lgkmcnt(3)
	v_mfma_f32_32x32x16_bf16 v[16:31], v[88:91], v[120:123], v[16:31]
	ds_read_b128 v[112:115], v74 offset:32
	ds_read_b128 v[116:119], v74 offset:4640
	ds_read_b128 v[120:123], v74 offset:9248
	ds_read_b128 v[128:131], v74 offset:13856
	ds_read_b128 v[132:135], v72 offset:36896
	s_waitcnt lgkmcnt(7)
	v_mfma_f32_32x32x16_bf16 v[0:15], v[88:91], v[124:127], v[0:15]
	v_readlane_b32 vcc_lo, v251, 23
	v_readlane_b32 vcc_hi, v251, 24
	s_waitcnt lgkmcnt(0)
	v_mfma_f32_32x32x16_bf16 v[48:63], v[132:135], v[112:115], v[48:63]
	global_load_dwordx4 v[112:115], v[68:69], off offset:512
	s_nop 1
	global_load_dwordx4 v[88:91], v66, vcc
	s_waitcnt vmcnt(6)
	ds_write_b128 v79, v[84:87]
	ds_write_b128 v80, v[100:103]
	v_mfma_f32_32x32x16_bf16 v[32:47], v[132:135], v[116:119], v[32:47]
	v_mfma_f32_32x32x16_bf16 v[16:31], v[132:135], v[120:123], v[16:31]
	ds_read_b128 v[84:87], v74 offset:64
	ds_read_b128 v[100:103], v74 offset:4672
	ds_read_b128 v[116:119], v74 offset:9280
	ds_read_b128 v[120:123], v74 offset:13888
	ds_read_b128 v[124:127], v72 offset:36928
	v_mfma_f32_32x32x16_bf16 v[0:15], v[132:135], v[128:131], v[0:15]
	v_readlane_b32 vcc_lo, v251, 25
	v_readlane_b32 vcc_hi, v251, 26
	s_waitcnt lgkmcnt(0)
	v_mfma_f32_32x32x16_bf16 v[48:63], v[124:127], v[84:87], v[48:63]
	s_waitcnt vmcnt(5)
	ds_write_b128 v81, v[92:95]
	s_nop 0
	global_load_dwordx4 v[84:87], v66, vcc
	v_mfma_f32_32x32x16_bf16 v[32:47], v[124:127], v[100:103], v[32:47]
	v_mfma_f32_32x32x16_bf16 v[16:31], v[124:127], v[116:119], v[16:31]
	ds_read_b128 v[92:95], v74 offset:96
	ds_read_b128 v[100:103], v74 offset:4704
	ds_read_b128 v[116:119], v74 offset:9312
	ds_read_b128 v[128:131], v74 offset:13920
	ds_read_b128 v[132:135], v72 offset:36960
	v_mfma_f32_32x32x16_bf16 v[0:15], v[124:127], v[120:123], v[0:15]
	v_readlane_b32 vcc_lo, v251, 27
	v_readlane_b32 vcc_hi, v251, 28
	s_waitcnt lgkmcnt(0)
	v_mfma_f32_32x32x16_bf16 v[48:63], v[132:135], v[92:95], v[48:63]
	s_waitcnt vmcnt(5)
	ds_write_b128 v82, v[96:99]
	s_nop 0
	global_load_dwordx4 v[92:95], v66, vcc
	v_mfma_f32_32x32x16_bf16 v[32:47], v[132:135], v[100:103], v[32:47]
	v_mfma_f32_32x32x16_bf16 v[16:31], v[132:135], v[116:119], v[16:31]
	v_mfma_f32_32x32x16_bf16 v[0:15], v[132:135], v[128:131], v[0:15]
	s_waitcnt lgkmcnt(0)
	s_barrier
; #define H_MMA(F) { _Pragma("unroll") for (int mb = 0; mb < 4; ++mb) acc[mb] = __builtin_amdgcn_mfma_f32_32x32x16_bf16(F[4], F[mb], acc[mb], 0, 0, 0); }
; DI void gemm_half_rowbf16(const bf16_t* __restrict__ A, int lda, const bf16_t* __restrict__ Bt, int ldb, int K, int m0, int n0, char* smem, bf16_t* __restrict__ Out, int ldo) {
;     ...
;   const int nk = K / 64;
;   H_LOADA(0, 0); H_LOADA(1, 0); H_LOADB(0, 0); H_LOADB(1, 0); H_LOADB(2, 0); H_LOADB(3, 0);
;   H_STOREA(0, 0); H_STOREA(0, 1); H_STOREB(0, 0); H_STOREB(0, 1); H_STOREB(0, 2); H_STOREB(0, 3);
;   if (nk > 1) { H_LOADA(0, 1); H_LOADA(1, 1); H_LOADB(0, 1); H_LOADB(1, 1); H_LOADB(2, 1); H_LOADB(3, 1); }
;   for (int kt = 0; kt < nk; ++kt) {
;     const int st = kt & 1;
;     __syncthreads();
;     bf16x8 f0[5], f1[5];
;     H_FRAGS(f0, st, 0);
;     H_PART(0, st, kt); H_FRAGS(f1, st, 1); H_MMA(f0); __builtin_amdgcn_sched_barrier(0);
;     H_PART(1, st, kt); H_FRAGS(f0, st, 2); H_MMA(f1); __builtin_amdgcn_sched_barrier(0);
;     H_PART(2, st, kt); H_FRAGS(f1, st, 3); H_MMA(f0); __builtin_amdgcn_sched_barrier(0);
;     H_PART(3, st, kt); H_MMA(f1); __builtin_amdgcn_sched_barrier(0);
;   }
	ds_read_b128 v[96:99], v75
	ds_read_b128 v[100:103], v76
	ds_read_b128 v[116:119], v76 offset:4608
	s_waitcnt lgkmcnt(1)
	v_mfma_f32_32x32x16_bf16 v[48:63], v[96:99], v[100:103], v[48:63]
	s_waitcnt lgkmcnt(0)
	v_mfma_f32_32x32x16_bf16 v[32:47], v[96:99], v[116:119], v[32:47]
	global_load_dwordx4 v[100:103], v66, s[4:5] offset:640
	global_load_dwordx4 v[116:119], v66, s[34:35] offset:640
	ds_read_b128 v[120:123], v76 offset:9216
	ds_read_b128 v[124:127], v76 offset:13824
	s_waitcnt vmcnt(7)
	ds_write_b128 v73, v[104:107] offset:36864
	s_waitcnt vmcnt(6)
	ds_write_b128 v73, v[108:111]
	s_waitcnt lgkmcnt(3)
	v_mfma_f32_32x32x16_bf16 v[16:31], v[96:99], v[120:123], v[16:31]
	ds_read_b128 v[104:107], v76 offset:32
	ds_read_b128 v[108:111], v76 offset:4640
	ds_read_b128 v[120:123], v76 offset:9248
	ds_read_b128 v[128:131], v76 offset:13856
	ds_read_b128 v[132:135], v75 offset:32
	s_waitcnt lgkmcnt(7)
	v_mfma_f32_32x32x16_bf16 v[0:15], v[96:99], v[124:127], v[0:15]
	v_readlane_b32 vcc_lo, v251, 29
	v_readlane_b32 vcc_hi, v251, 30
	s_waitcnt lgkmcnt(0)
	v_mfma_f32_32x32x16_bf16 v[48:63], v[132:135], v[104:107], v[48:63]
	global_load_dwordx4 v[104:107], v[68:69], off offset:640
	s_nop 1
	global_load_dwordx4 v[96:99], v66, vcc
	s_waitcnt vmcnt(6)
	ds_write_b128 v73, v[88:91] offset:46080
	ds_write_b128 v73, v[112:115] offset:9216
	v_mfma_f32_32x32x16_bf16 v[32:47], v[132:135], v[108:111], v[32:47]
	v_mfma_f32_32x32x16_bf16 v[16:31], v[132:135], v[120:123], v[16:31]
	ds_read_b128 v[88:91], v76 offset:64
	ds_read_b128 v[108:111], v76 offset:4672
	ds_read_b128 v[112:115], v76 offset:9280
	ds_read_b128 v[120:123], v76 offset:13888
	ds_read_b128 v[124:127], v75 offset:64
	v_mfma_f32_32x32x16_bf16 v[0:15], v[132:135], v[128:131], v[0:15]
	v_readlane_b32 vcc_lo, v251, 31
	v_readlane_b32 vcc_hi, v251, 32
	s_waitcnt lgkmcnt(0)
	v_mfma_f32_32x32x16_bf16 v[48:63], v[124:127], v[88:91], v[48:63]
	s_waitcnt vmcnt(5)
	ds_write_b128 v73, v[84:87] offset:55296
	s_nop 0
	global_load_dwordx4 v[88:91], v66, vcc
	v_mfma_f32_32x32x16_bf16 v[32:47], v[124:127], v[108:111], v[32:47]
	v_mfma_f32_32x32x16_bf16 v[16:31], v[124:127], v[112:115], v[16:31]
	ds_read_b128 v[84:87], v76 offset:96
	ds_read_b128 v[108:111], v76 offset:4704
	ds_read_b128 v[112:115], v76 offset:9312
	ds_read_b128 v[128:131], v76 offset:13920
	ds_read_b128 v[132:135], v75 offset:96
	v_mfma_f32_32x32x16_bf16 v[0:15], v[124:127], v[120:123], v[0:15]
	v_readlane_b32 vcc_lo, v251, 33
	v_readlane_b32 vcc_hi, v251, 34
	s_waitcnt lgkmcnt(0)
	v_mfma_f32_32x32x16_bf16 v[48:63], v[132:135], v[84:87], v[48:63]
	s_waitcnt vmcnt(5)
	ds_write_b128 v73, v[92:95] offset:64512
	s_nop 0
	global_load_dwordx4 v[84:87], v66, vcc
	v_mfma_f32_32x32x16_bf16 v[32:47], v[132:135], v[108:111], v[32:47]
	v_mfma_f32_32x32x16_bf16 v[16:31], v[132:135], v[112:115], v[16:31]
	v_mfma_f32_32x32x16_bf16 v[0:15], v[132:135], v[128:131], v[0:15]
	s_waitcnt lgkmcnt(0)
	s_barrier
	ds_read_b128 v[92:95], v72 offset:36864
	ds_read_b128 v[108:111], v74
	ds_read_b128 v[112:115], v74 offset:4608
	s_waitcnt lgkmcnt(1)
	v_mfma_f32_32x32x16_bf16 v[48:63], v[92:95], v[108:111], v[48:63]
	s_waitcnt lgkmcnt(0)
	v_mfma_f32_32x32x16_bf16 v[32:47], v[92:95], v[112:115], v[32:47]
	global_load_dwordx4 v[108:111], v66, s[4:5] offset:768
	global_load_dwordx4 v[112:115], v66, s[34:35] offset:768
	ds_read_b128 v[120:123], v74 offset:9216
	ds_read_b128 v[124:127], v74 offset:13824
	s_waitcnt vmcnt(7)
	ds_write_b128 v77, v[100:103]
	s_waitcnt vmcnt(6)
	ds_write_b128 v78, v[116:119]
	s_waitcnt lgkmcnt(3)
	v_mfma_f32_32x32x16_bf16 v[16:31], v[92:95], v[120:123], v[16:31]
	ds_read_b128 v[100:103], v74 offset:32
	ds_read_b128 v[116:119], v74 offset:4640
	ds_read_b128 v[120:123], v74 offset:9248
	ds_read_b128 v[128:131], v74 offset:13856
	ds_read_b128 v[132:135], v72 offset:36896
	s_waitcnt lgkmcnt(7)
	v_mfma_f32_32x32x16_bf16 v[0:15], v[92:95], v[124:127], v[0:15]
	v_readlane_b32 vcc_lo, v251, 35
	v_readlane_b32 vcc_hi, v251, 36
	s_waitcnt lgkmcnt(0)
	v_mfma_f32_32x32x16_bf16 v[48:63], v[132:135], v[100:103], v[48:63]
	global_load_dwordx4 v[100:103], v[68:69], off offset:768
	s_nop 1
	global_load_dwordx4 v[92:95], v66, vcc
	s_waitcnt vmcnt(6)
	ds_write_b128 v79, v[96:99]
	ds_write_b128 v80, v[104:107]
	v_mfma_f32_32x32x16_bf16 v[32:47], v[132:135], v[116:119], v[32:47]
	v_mfma_f32_32x32x16_bf16 v[16:31], v[132:135], v[120:123], v[16:31]
	ds_read_b128 v[96:99], v74 offset:64
	ds_read_b128 v[104:107], v74 offset:4672
	ds_read_b128 v[116:119], v74 offset:9280
	ds_read_b128 v[120:123], v74 offset:13888
	ds_read_b128 v[124:127], v72 offset:36928
	v_mfma_f32_32x32x16_bf16 v[0:15], v[132:135], v[128:131], v[0:15]
	v_readlane_b32 vcc_lo, v251, 37
	v_readlane_b32 vcc_hi, v251, 38
	s_waitcnt lgkmcnt(0)
	v_mfma_f32_32x32x16_bf16 v[48:63], v[124:127], v[96:99], v[48:63]
	s_waitcnt vmcnt(5)
	ds_write_b128 v81, v[88:91]
	s_nop 0
	global_load_dwordx4 v[96:99], v66, vcc
	v_mfma_f32_32x32x16_bf16 v[32:47], v[124:127], v[104:107], v[32:47]
	v_mfma_f32_32x32x16_bf16 v[16:31], v[124:127], v[116:119], v[16:31]
	ds_read_b128 v[88:91], v74 offset:96
	ds_read_b128 v[104:107], v74 offset:4704
	ds_read_b128 v[116:119], v74 offset:9312
	ds_read_b128 v[128:131], v74 offset:13920
	ds_read_b128 v[132:135], v72 offset:36960
	v_mfma_f32_32x32x16_bf16 v[0:15], v[124:127], v[120:123], v[0:15]
	v_readlane_b32 vcc_lo, v251, 39
	v_readlane_b32 vcc_hi, v251, 40
	s_waitcnt lgkmcnt(0)
	v_mfma_f32_32x32x16_bf16 v[48:63], v[132:135], v[88:91], v[48:63]
	s_waitcnt vmcnt(5)
	ds_write_b128 v82, v[84:87]
	s_nop 0
	global_load_dwordx4 v[88:91], v66, vcc
	v_mfma_f32_32x32x16_bf16 v[32:47], v[132:135], v[104:107], v[32:47]
	v_mfma_f32_32x32x16_bf16 v[16:31], v[132:135], v[116:119], v[16:31]
	v_mfma_f32_32x32x16_bf16 v[0:15], v[132:135], v[128:131], v[0:15]
	s_waitcnt lgkmcnt(0)
	s_barrier
; #define H_MMA(F) { _Pragma("unroll") for (int mb = 0; mb < 4; ++mb) acc[mb] = __builtin_amdgcn_mfma_f32_32x32x16_bf16(F[4], F[mb], acc[mb], 0, 0, 0); }
; DI void gemm_half_rowbf16(const bf16_t* __restrict__ A, int lda, const bf16_t* __restrict__ Bt, int ldb, int K, int m0, int n0, char* smem, bf16_t* __restrict__ Out, int ldo) {
;     ...
;   const int nk = K / 64;
;   H_LOADA(0, 0); H_LOADA(1, 0); H_LOADB(0, 0); H_LOADB(1, 0); H_LOADB(2, 0); H_LOADB(3, 0);
;   H_STOREA(0, 0); H_STOREA(0, 1); H_STOREB(0, 0); H_STOREB(0, 1); H_STOREB(0, 2); H_STOREB(0, 3);
;   if (nk > 1) { H_LOADA(0, 1); H_LOADA(1, 1); H_LOADB(0, 1); H_LOADB(1, 1); H_LOADB(2, 1); H_LOADB(3, 1); }
;   for (int kt = 0; kt < nk; ++kt) {
;     const int st = kt & 1;
;     __syncthreads();
;     bf16x8 f0[5], f1[5];
;     H_FRAGS(f0, st, 0);
;     H_PART(0, st, kt); H_FRAGS(f1, st, 1); H_MMA(f0); __builtin_amdgcn_sched_barrier(0);
;     H_PART(1, st, kt); H_FRAGS(f0, st, 2); H_MMA(f1); __builtin_amdgcn_sched_barrier(0);
;     H_PART(2, st, kt); H_FRAGS(f1, st, 3); H_MMA(f0); __builtin_amdgcn_sched_barrier(0);
;     H_PART(3, st, kt); H_MMA(f1); __builtin_amdgcn_sched_barrier(0);
;   }
	ds_read_b128 v[84:87], v75
	ds_read_b128 v[104:107], v76
	ds_read_b128 v[116:119], v76 offset:4608
	s_waitcnt lgkmcnt(1)
	v_mfma_f32_32x32x16_bf16 v[48:63], v[84:87], v[104:107], v[48:63]
	s_waitcnt lgkmcnt(0)
	v_mfma_f32_32x32x16_bf16 v[32:47], v[84:87], v[116:119], v[32:47]
	global_load_dwordx4 v[104:107], v66, s[4:5] offset:896
	global_load_dwordx4 v[116:119], v66, s[34:35] offset:896
	ds_read_b128 v[120:123], v76 offset:9216
	ds_read_b128 v[124:127], v76 offset:13824
	s_waitcnt vmcnt(7)
	ds_write_b128 v73, v[108:111] offset:36864
	s_waitcnt vmcnt(6)
	ds_write_b128 v73, v[112:115]
	s_waitcnt lgkmcnt(3)
	v_mfma_f32_32x32x16_bf16 v[16:31], v[84:87], v[120:123], v[16:31]
	ds_read_b128 v[108:111], v76 offset:32
	ds_read_b128 v[112:115], v76 offset:4640
	ds_read_b128 v[120:123], v76 offset:9248
	ds_read_b128 v[128:131], v76 offset:13856
	ds_read_b128 v[132:135], v75 offset:32
	s_waitcnt lgkmcnt(7)
	v_mfma_f32_32x32x16_bf16 v[0:15], v[84:87], v[124:127], v[0:15]
	v_readlane_b32 vcc_lo, v251, 41
	v_readlane_b32 vcc_hi, v251, 42
	s_waitcnt lgkmcnt(0)
	v_mfma_f32_32x32x16_bf16 v[48:63], v[132:135], v[108:111], v[48:63]
	global_load_dwordx4 v[108:111], v[68:69], off offset:896
	s_nop 1
	global_load_dwordx4 v[84:87], v66, vcc
	s_waitcnt vmcnt(6)
	ds_write_b128 v73, v[92:95] offset:46080
	ds_write_b128 v73, v[100:103] offset:9216
	v_mfma_f32_32x32x16_bf16 v[32:47], v[132:135], v[112:115], v[32:47]
	v_mfma_f32_32x32x16_bf16 v[16:31], v[132:135], v[120:123], v[16:31]
	ds_read_b128 v[92:95], v76 offset:64
	ds_read_b128 v[100:103], v76 offset:4672
	ds_read_b128 v[112:115], v76 offset:9280
	ds_read_b128 v[120:123], v76 offset:13888
	ds_read_b128 v[124:127], v75 offset:64
	v_mfma_f32_32x32x16_bf16 v[0:15], v[132:135], v[128:131], v[0:15]
	v_readlane_b32 vcc_lo, v251, 43
	v_readlane_b32 vcc_hi, v251, 44
	s_waitcnt lgkmcnt(0)
	v_mfma_f32_32x32x16_bf16 v[48:63], v[124:127], v[92:95], v[48:63]
	s_waitcnt vmcnt(5)
	ds_write_b128 v73, v[96:99] offset:55296
	s_nop 0
	global_load_dwordx4 v[92:95], v66, vcc
	v_mfma_f32_32x32x16_bf16 v[32:47], v[124:127], v[100:103], v[32:47]
	v_mfma_f32_32x32x16_bf16 v[16:31], v[124:127], v[112:115], v[16:31]
	ds_read_b128 v[96:99], v76 offset:96
	ds_read_b128 v[100:103], v76 offset:4704
	ds_read_b128 v[112:115], v76 offset:9312
	ds_read_b128 v[128:131], v76 offset:13920
	ds_read_b128 v[132:135], v75 offset:96
	v_mfma_f32_32x32x16_bf16 v[0:15], v[124:127], v[120:123], v[0:15]
	v_readlane_b32 vcc_lo, v251, 45
	v_readlane_b32 vcc_hi, v251, 46
	s_waitcnt lgkmcnt(0)
	v_mfma_f32_32x32x16_bf16 v[48:63], v[132:135], v[96:99], v[48:63]
	s_waitcnt vmcnt(5)
	ds_write_b128 v73, v[88:91] offset:64512
	s_nop 0
	global_load_dwordx4 v[96:99], v66, vcc
	v_mfma_f32_32x32x16_bf16 v[32:47], v[132:135], v[100:103], v[32:47]
	v_mfma_f32_32x32x16_bf16 v[16:31], v[132:135], v[112:115], v[16:31]
	v_mfma_f32_32x32x16_bf16 v[0:15], v[132:135], v[128:131], v[0:15]
	s_waitcnt lgkmcnt(0)
	s_barrier
	ds_read_b128 v[88:91], v72 offset:36864
	ds_read_b128 v[100:103], v74
	ds_read_b128 v[112:115], v74 offset:4608
	s_waitcnt lgkmcnt(1)
	v_mfma_f32_32x32x16_bf16 v[48:63], v[88:91], v[100:103], v[48:63]
	s_waitcnt lgkmcnt(0)
	v_mfma_f32_32x32x16_bf16 v[32:47], v[88:91], v[112:115], v[32:47]
	global_load_dwordx4 v[100:103], v66, s[4:5] offset:1024
	global_load_dwordx4 v[112:115], v66, s[34:35] offset:1024
	ds_read_b128 v[120:123], v74 offset:9216
	ds_read_b128 v[124:127], v74 offset:13824
	s_waitcnt vmcnt(7)
	ds_write_b128 v77, v[104:107]
	s_waitcnt vmcnt(6)
	ds_write_b128 v78, v[116:119]
	s_waitcnt lgkmcnt(3)
	v_mfma_f32_32x32x16_bf16 v[16:31], v[88:91], v[120:123], v[16:31]
	ds_read_b128 v[104:107], v74 offset:32
	ds_read_b128 v[116:119], v74 offset:4640
	ds_read_b128 v[120:123], v74 offset:9248
	ds_read_b128 v[128:131], v74 offset:13856
	ds_read_b128 v[132:135], v72 offset:36896
	s_waitcnt lgkmcnt(7)
	v_mfma_f32_32x32x16_bf16 v[0:15], v[88:91], v[124:127], v[0:15]
	v_readlane_b32 vcc_lo, v251, 47
	v_readlane_b32 vcc_hi, v251, 48
	s_waitcnt lgkmcnt(0)
	v_mfma_f32_32x32x16_bf16 v[48:63], v[132:135], v[104:107], v[48:63]
	global_load_dwordx4 v[104:107], v[68:69], off offset:1024
	s_nop 1
	global_load_dwordx4 v[88:91], v66, vcc
	s_waitcnt vmcnt(6)
	ds_write_b128 v79, v[84:87]
	ds_write_b128 v80, v[108:111]
	v_mfma_f32_32x32x16_bf16 v[32:47], v[132:135], v[116:119], v[32:47]
	v_mfma_f32_32x32x16_bf16 v[16:31], v[132:135], v[120:123], v[16:31]
	ds_read_b128 v[84:87], v74 offset:64
	ds_read_b128 v[108:111], v74 offset:4672
	ds_read_b128 v[116:119], v74 offset:9280
	ds_read_b128 v[120:123], v74 offset:13888
	ds_read_b128 v[124:127], v72 offset:36928
	v_mfma_f32_32x32x16_bf16 v[0:15], v[132:135], v[128:131], v[0:15]
	v_readlane_b32 vcc_lo, v251, 49
	v_readlane_b32 vcc_hi, v251, 50
	s_waitcnt lgkmcnt(0)
	v_mfma_f32_32x32x16_bf16 v[48:63], v[124:127], v[84:87], v[48:63]
	s_waitcnt vmcnt(5)
	ds_write_b128 v81, v[92:95]
	s_nop 0
	global_load_dwordx4 v[84:87], v66, vcc
	v_mfma_f32_32x32x16_bf16 v[32:47], v[124:127], v[108:111], v[32:47]
	v_mfma_f32_32x32x16_bf16 v[16:31], v[124:127], v[116:119], v[16:31]
	ds_read_b128 v[92:95], v74 offset:96
	ds_read_b128 v[108:111], v74 offset:4704
	ds_read_b128 v[116:119], v74 offset:9312
	ds_read_b128 v[128:131], v74 offset:13920
	ds_read_b128 v[132:135], v72 offset:36960
	v_mfma_f32_32x32x16_bf16 v[0:15], v[124:127], v[120:123], v[0:15]
	v_readlane_b32 vcc_lo, v251, 51
	v_readlane_b32 vcc_hi, v251, 52
	s_waitcnt lgkmcnt(0)
	v_mfma_f32_32x32x16_bf16 v[48:63], v[132:135], v[92:95], v[48:63]
	s_waitcnt vmcnt(5)
	ds_write_b128 v82, v[96:99]
	s_nop 0
	global_load_dwordx4 v[92:95], v66, vcc
	v_mfma_f32_32x32x16_bf16 v[32:47], v[132:135], v[108:111], v[32:47]
	v_mfma_f32_32x32x16_bf16 v[16:31], v[132:135], v[116:119], v[16:31]
	v_mfma_f32_32x32x16_bf16 v[0:15], v[132:135], v[128:131], v[0:15]
	s_waitcnt lgkmcnt(0)
	s_barrier
; #define H_MMA(F) { _Pragma("unroll") for (int mb = 0; mb < 4; ++mb) acc[mb] = __builtin_amdgcn_mfma_f32_32x32x16_bf16(F[4], F[mb], acc[mb], 0, 0, 0); }
; DI void gemm_half_rowbf16(const bf16_t* __restrict__ A, int lda, const bf16_t* __restrict__ Bt, int ldb, int K, int m0, int n0, char* smem, bf16_t* __restrict__ Out, int ldo) {
;     ...
;   const int nk = K / 64;
;   H_LOADA(0, 0); H_LOADA(1, 0); H_LOADB(0, 0); H_LOADB(1, 0); H_LOADB(2, 0); H_LOADB(3, 0);
;   H_STOREA(0, 0); H_STOREA(0, 1); H_STOREB(0, 0); H_STOREB(0, 1); H_STOREB(0, 2); H_STOREB(0, 3);
;   if (nk > 1) { H_LOADA(0, 1); H_LOADA(1, 1); H_LOADB(0, 1); H_LOADB(1, 1); H_LOADB(2, 1); H_LOADB(3, 1); }
;   for (int kt = 0; kt < nk; ++kt) {
;     const int st = kt & 1;
;     __syncthreads();
;     bf16x8 f0[5], f1[5];
;     H_FRAGS(f0, st, 0);
;     H_PART(0, st, kt); H_FRAGS(f1, st, 1); H_MMA(f0); __builtin_amdgcn_sched_barrier(0);
;     H_PART(1, st, kt); H_FRAGS(f0, st, 2); H_MMA(f1); __builtin_amdgcn_sched_barrier(0);
;     H_PART(2, st, kt); H_FRAGS(f1, st, 3); H_MMA(f0); __builtin_amdgcn_sched_barrier(0);
;     H_PART(3, st, kt); H_MMA(f1); __builtin_amdgcn_sched_barrier(0);
;   }
	ds_read_b128 v[96:99], v75
	ds_read_b128 v[108:111], v76
	ds_read_b128 v[116:119], v76 offset:4608
	s_waitcnt lgkmcnt(1)
	v_mfma_f32_32x32x16_bf16 v[48:63], v[96:99], v[108:111], v[48:63]
	s_waitcnt lgkmcnt(0)
	v_mfma_f32_32x32x16_bf16 v[32:47], v[96:99], v[116:119], v[32:47]
	global_load_dwordx4 v[108:111], v66, s[4:5] offset:1152
	global_load_dwordx4 v[116:119], v66, s[34:35] offset:1152
	ds_read_b128 v[120:123], v76 offset:9216
	ds_read_b128 v[124:127], v76 offset:13824
	s_waitcnt vmcnt(7)
	ds_write_b128 v73, v[100:103] offset:36864
	s_waitcnt vmcnt(6)
	ds_write_b128 v73, v[112:115]
	s_waitcnt lgkmcnt(3)
	v_mfma_f32_32x32x16_bf16 v[16:31], v[96:99], v[120:123], v[16:31]
	ds_read_b128 v[100:103], v76 offset:32
	ds_read_b128 v[112:115], v76 offset:4640
	ds_read_b128 v[120:123], v76 offset:9248
	ds_read_b128 v[128:131], v76 offset:13856
	ds_read_b128 v[132:135], v75 offset:32
	s_waitcnt lgkmcnt(7)
	v_mfma_f32_32x32x16_bf16 v[0:15], v[96:99], v[124:127], v[0:15]
	v_readlane_b32 vcc_lo, v251, 53
	v_readlane_b32 vcc_hi, v251, 54
	s_waitcnt lgkmcnt(0)
	v_mfma_f32_32x32x16_bf16 v[48:63], v[132:135], v[100:103], v[48:63]
	global_load_dwordx4 v[100:103], v[68:69], off offset:1152
	s_nop 1
	global_load_dwordx4 v[96:99], v66, vcc
	s_waitcnt vmcnt(6)
	ds_write_b128 v73, v[88:91] offset:46080
	ds_write_b128 v73, v[104:107] offset:9216
	v_mfma_f32_32x32x16_bf16 v[32:47], v[132:135], v[112:115], v[32:47]
	v_mfma_f32_32x32x16_bf16 v[16:31], v[132:135], v[120:123], v[16:31]
	ds_read_b128 v[88:91], v76 offset:64
	ds_read_b128 v[104:107], v76 offset:4672
	ds_read_b128 v[112:115], v76 offset:9280
	ds_read_b128 v[120:123], v76 offset:13888
	ds_read_b128 v[124:127], v75 offset:64
	v_mfma_f32_32x32x16_bf16 v[0:15], v[132:135], v[128:131], v[0:15]
	v_readlane_b32 vcc_lo, v251, 55
	v_readlane_b32 vcc_hi, v251, 56
	s_waitcnt lgkmcnt(0)
	v_mfma_f32_32x32x16_bf16 v[48:63], v[124:127], v[88:91], v[48:63]
	s_waitcnt vmcnt(5)
	ds_write_b128 v73, v[84:87] offset:55296
	s_nop 0
	global_load_dwordx4 v[88:91], v66, vcc
	v_mfma_f32_32x32x16_bf16 v[32:47], v[124:127], v[104:107], v[32:47]
	v_mfma_f32_32x32x16_bf16 v[16:31], v[124:127], v[112:115], v[16:31]
	ds_read_b128 v[84:87], v76 offset:96
	ds_read_b128 v[104:107], v76 offset:4704
	ds_read_b128 v[112:115], v76 offset:9312
	ds_read_b128 v[128:131], v76 offset:13920
	ds_read_b128 v[132:135], v75 offset:96
	v_mfma_f32_32x32x16_bf16 v[0:15], v[124:127], v[120:123], v[0:15]
	v_readlane_b32 vcc_lo, v251, 57
	v_readlane_b32 vcc_hi, v251, 58
	s_waitcnt lgkmcnt(0)
	v_mfma_f32_32x32x16_bf16 v[48:63], v[132:135], v[84:87], v[48:63]
	s_waitcnt vmcnt(5)
	ds_write_b128 v73, v[92:95] offset:64512
	s_nop 0
	global_load_dwordx4 v[84:87], v66, vcc
	v_mfma_f32_32x32x16_bf16 v[32:47], v[132:135], v[104:107], v[32:47]
	v_mfma_f32_32x32x16_bf16 v[16:31], v[132:135], v[112:115], v[16:31]
	v_mfma_f32_32x32x16_bf16 v[0:15], v[132:135], v[128:131], v[0:15]
	s_waitcnt lgkmcnt(0)
	s_barrier
	ds_read_b128 v[92:95], v72 offset:36864
	ds_read_b128 v[104:107], v74
	ds_read_b128 v[112:115], v74 offset:4608
	s_waitcnt lgkmcnt(1)
	v_mfma_f32_32x32x16_bf16 v[48:63], v[92:95], v[104:107], v[48:63]
	s_waitcnt lgkmcnt(0)
	v_mfma_f32_32x32x16_bf16 v[32:47], v[92:95], v[112:115], v[32:47]
	global_load_dwordx4 v[104:107], v66, s[4:5] offset:1280
	global_load_dwordx4 v[112:115], v66, s[34:35] offset:1280
	ds_read_b128 v[120:123], v74 offset:9216
	ds_read_b128 v[124:127], v74 offset:13824
	s_waitcnt vmcnt(7)
	ds_write_b128 v77, v[108:111]
	s_waitcnt vmcnt(6)
	ds_write_b128 v78, v[116:119]
	s_waitcnt lgkmcnt(3)
	v_mfma_f32_32x32x16_bf16 v[16:31], v[92:95], v[120:123], v[16:31]
	ds_read_b128 v[108:111], v74 offset:32
	ds_read_b128 v[116:119], v74 offset:4640
	ds_read_b128 v[120:123], v74 offset:9248
	ds_read_b128 v[128:131], v74 offset:13856
	ds_read_b128 v[132:135], v72 offset:36896
	s_waitcnt lgkmcnt(7)
	v_mfma_f32_32x32x16_bf16 v[0:15], v[92:95], v[124:127], v[0:15]
	v_readlane_b32 vcc_lo, v251, 59
	v_readlane_b32 vcc_hi, v251, 60
	s_waitcnt lgkmcnt(0)
	v_mfma_f32_32x32x16_bf16 v[48:63], v[132:135], v[108:111], v[48:63]
	global_load_dwordx4 v[108:111], v[68:69], off offset:1280
	s_nop 1
	global_load_dwordx4 v[92:95], v66, vcc
	s_waitcnt vmcnt(6)
	ds_write_b128 v79, v[96:99]
	ds_write_b128 v80, v[100:103]
	v_mfma_f32_32x32x16_bf16 v[32:47], v[132:135], v[116:119], v[32:47]
	v_mfma_f32_32x32x16_bf16 v[16:31], v[132:135], v[120:123], v[16:31]
	ds_read_b128 v[96:99], v74 offset:64
	ds_read_b128 v[100:103], v74 offset:4672
	ds_read_b128 v[116:119], v74 offset:9280
	ds_read_b128 v[120:123], v74 offset:13888
	ds_read_b128 v[124:127], v72 offset:36928
	v_mfma_f32_32x32x16_bf16 v[0:15], v[132:135], v[128:131], v[0:15]
	v_readlane_b32 vcc_lo, v251, 61
	v_readlane_b32 vcc_hi, v251, 62
	s_waitcnt lgkmcnt(0)
	v_mfma_f32_32x32x16_bf16 v[48:63], v[124:127], v[96:99], v[48:63]
	s_waitcnt vmcnt(5)
	ds_write_b128 v81, v[88:91]
	s_nop 0
	global_load_dwordx4 v[96:99], v66, vcc
	v_mfma_f32_32x32x16_bf16 v[32:47], v[124:127], v[100:103], v[32:47]
	v_mfma_f32_32x32x16_bf16 v[16:31], v[124:127], v[116:119], v[16:31]
	ds_read_b128 v[88:91], v74 offset:96
	ds_read_b128 v[100:103], v74 offset:4704
	ds_read_b128 v[116:119], v74 offset:9312
	ds_read_b128 v[128:131], v74 offset:13920
	ds_read_b128 v[132:135], v72 offset:36960
	v_mfma_f32_32x32x16_bf16 v[0:15], v[124:127], v[120:123], v[0:15]
	v_readlane_b32 vcc_lo, v251, 63
	v_readlane_b32 vcc_hi, v250, 0
	s_waitcnt lgkmcnt(0)
	v_mfma_f32_32x32x16_bf16 v[48:63], v[132:135], v[88:91], v[48:63]
	s_waitcnt vmcnt(5)
	ds_write_b128 v82, v[84:87]
	s_nop 0
	global_load_dwordx4 v[88:91], v66, vcc
	v_mfma_f32_32x32x16_bf16 v[32:47], v[132:135], v[100:103], v[32:47]
	v_mfma_f32_32x32x16_bf16 v[16:31], v[132:135], v[116:119], v[16:31]
	v_mfma_f32_32x32x16_bf16 v[0:15], v[132:135], v[128:131], v[0:15]
	s_waitcnt lgkmcnt(0)
	s_barrier
; #define H_MMA(F) { _Pragma("unroll") for (int mb = 0; mb < 4; ++mb) acc[mb] = __builtin_amdgcn_mfma_f32_32x32x16_bf16(F[4], F[mb], acc[mb], 0, 0, 0); }
; DI void gemm_half_rowbf16(const bf16_t* __restrict__ A, int lda, const bf16_t* __restrict__ Bt, int ldb, int K, int m0, int n0, char* smem, bf16_t* __restrict__ Out, int ldo) {
;     ...
;   const int nk = K / 64;
;   H_LOADA(0, 0); H_LOADA(1, 0); H_LOADB(0, 0); H_LOADB(1, 0); H_LOADB(2, 0); H_LOADB(3, 0);
;   H_STOREA(0, 0); H_STOREA(0, 1); H_STOREB(0, 0); H_STOREB(0, 1); H_STOREB(0, 2); H_STOREB(0, 3);
;   if (nk > 1) { H_LOADA(0, 1); H_LOADA(1, 1); H_LOADB(0, 1); H_LOADB(1, 1); H_LOADB(2, 1); H_LOADB(3, 1); }
;   for (int kt = 0; kt < nk; ++kt) {
;     const int st = kt & 1;
;     __syncthreads();
;     bf16x8 f0[5], f1[5];
;     H_FRAGS(f0, st, 0);
;     H_PART(0, st, kt); H_FRAGS(f1, st, 1); H_MMA(f0); __builtin_amdgcn_sched_barrier(0);
;     H_PART(1, st, kt); H_FRAGS(f0, st, 2); H_MMA(f1); __builtin_amdgcn_sched_barrier(0);
;     H_PART(2, st, kt); H_FRAGS(f1, st, 3); H_MMA(f0); __builtin_amdgcn_sched_barrier(0);
;     H_PART(3, st, kt); H_MMA(f1); __builtin_amdgcn_sched_barrier(0);
;   }
	ds_read_b128 v[84:87], v75
	ds_read_b128 v[100:103], v76
	ds_read_b128 v[116:119], v76 offset:4608
	s_waitcnt lgkmcnt(1)
	v_mfma_f32_32x32x16_bf16 v[48:63], v[84:87], v[100:103], v[48:63]
	s_waitcnt lgkmcnt(0)
	v_mfma_f32_32x32x16_bf16 v[32:47], v[84:87], v[116:119], v[32:47]
	global_load_dwordx4 v[100:103], v66, s[4:5] offset:1408
	global_load_dwordx4 v[116:119], v66, s[34:35] offset:1408
	ds_read_b128 v[120:123], v76 offset:9216
	ds_read_b128 v[124:127], v76 offset:13824
	s_waitcnt vmcnt(7)
	ds_write_b128 v73, v[104:107] offset:36864
	s_waitcnt vmcnt(6)
	ds_write_b128 v73, v[112:115]
	s_waitcnt lgkmcnt(3)
	v_mfma_f32_32x32x16_bf16 v[16:31], v[84:87], v[120:123], v[16:31]
	ds_read_b128 v[104:107], v76 offset:32
	ds_read_b128 v[112:115], v76 offset:4640
	ds_read_b128 v[120:123], v76 offset:9248
	ds_read_b128 v[128:131], v76 offset:13856
	ds_read_b128 v[132:135], v75 offset:32
	s_waitcnt lgkmcnt(7)
	v_mfma_f32_32x32x16_bf16 v[0:15], v[84:87], v[124:127], v[0:15]
	v_readlane_b32 vcc_lo, v250, 1
	v_readlane_b32 vcc_hi, v250, 2
	s_waitcnt lgkmcnt(0)
	v_mfma_f32_32x32x16_bf16 v[48:63], v[132:135], v[104:107], v[48:63]
	global_load_dwordx4 v[104:107], v[68:69], off offset:1408
	s_nop 1
	global_load_dwordx4 v[84:87], v66, vcc
	s_waitcnt vmcnt(6)
	ds_write_b128 v73, v[92:95] offset:46080
	ds_write_b128 v73, v[108:111] offset:9216
	v_mfma_f32_32x32x16_bf16 v[32:47], v[132:135], v[112:115], v[32:47]
	v_mfma_f32_32x32x16_bf16 v[16:31], v[132:135], v[120:123], v[16:31]
	ds_read_b128 v[92:95], v76 offset:64
	ds_read_b128 v[108:111], v76 offset:4672
	ds_read_b128 v[112:115], v76 offset:9280
	ds_read_b128 v[120:123], v76 offset:13888
	ds_read_b128 v[124:127], v75 offset:64
	v_mfma_f32_32x32x16_bf16 v[0:15], v[132:135], v[128:131], v[0:15]
	v_readlane_b32 vcc_lo, v250, 3
	v_readlane_b32 vcc_hi, v250, 4
	s_waitcnt lgkmcnt(0)
	v_mfma_f32_32x32x16_bf16 v[48:63], v[124:127], v[92:95], v[48:63]
	s_waitcnt vmcnt(5)
	ds_write_b128 v73, v[96:99] offset:55296
	s_nop 0
	global_load_dwordx4 v[92:95], v66, vcc
	v_mfma_f32_32x32x16_bf16 v[32:47], v[124:127], v[108:111], v[32:47]
	v_mfma_f32_32x32x16_bf16 v[16:31], v[124:127], v[112:115], v[16:31]
	ds_read_b128 v[96:99], v76 offset:96
	ds_read_b128 v[108:111], v76 offset:4704
	ds_read_b128 v[112:115], v76 offset:9312
	ds_read_b128 v[128:131], v76 offset:13920
	ds_read_b128 v[132:135], v75 offset:96
	v_mfma_f32_32x32x16_bf16 v[0:15], v[124:127], v[120:123], v[0:15]
	v_readlane_b32 vcc_lo, v250, 5
	v_readlane_b32 vcc_hi, v250, 6
	s_waitcnt lgkmcnt(0)
	v_mfma_f32_32x32x16_bf16 v[48:63], v[132:135], v[96:99], v[48:63]
	s_waitcnt vmcnt(5)
	ds_write_b128 v73, v[88:91] offset:64512
	s_nop 0
	global_load_dwordx4 v[96:99], v66, vcc
	v_mfma_f32_32x32x16_bf16 v[32:47], v[132:135], v[108:111], v[32:47]
	v_mfma_f32_32x32x16_bf16 v[16:31], v[132:135], v[112:115], v[16:31]
	v_mfma_f32_32x32x16_bf16 v[0:15], v[132:135], v[128:131], v[0:15]
	s_waitcnt lgkmcnt(0)
	s_barrier
	ds_read_b128 v[88:91], v72 offset:36864
	ds_read_b128 v[108:111], v74
	ds_read_b128 v[112:115], v74 offset:4608
	s_waitcnt lgkmcnt(1)
	v_mfma_f32_32x32x16_bf16 v[48:63], v[88:91], v[108:111], v[48:63]
	s_waitcnt lgkmcnt(0)
	v_mfma_f32_32x32x16_bf16 v[32:47], v[88:91], v[112:115], v[32:47]
	global_load_dwordx4 v[108:111], v66, s[4:5] offset:1536
	global_load_dwordx4 v[112:115], v66, s[34:35] offset:1536
	ds_read_b128 v[120:123], v74 offset:9216
	ds_read_b128 v[124:127], v74 offset:13824
	s_waitcnt vmcnt(7)
	ds_write_b128 v77, v[100:103]
	s_waitcnt vmcnt(6)
	ds_write_b128 v78, v[116:119]
	s_waitcnt lgkmcnt(3)
	v_mfma_f32_32x32x16_bf16 v[16:31], v[88:91], v[120:123], v[16:31]
	ds_read_b128 v[100:103], v74 offset:32
	ds_read_b128 v[116:119], v74 offset:4640
	ds_read_b128 v[120:123], v74 offset:9248
	ds_read_b128 v[128:131], v74 offset:13856
	ds_read_b128 v[132:135], v72 offset:36896
	s_waitcnt lgkmcnt(7)
	v_mfma_f32_32x32x16_bf16 v[0:15], v[88:91], v[124:127], v[0:15]
	v_readlane_b32 vcc_lo, v250, 7
	v_readlane_b32 vcc_hi, v250, 8
	s_waitcnt lgkmcnt(0)
	v_mfma_f32_32x32x16_bf16 v[48:63], v[132:135], v[100:103], v[48:63]
	global_load_dwordx4 v[100:103], v[68:69], off offset:1536
	s_nop 1
	global_load_dwordx4 v[88:91], v66, vcc
	s_waitcnt vmcnt(6)
	ds_write_b128 v79, v[84:87]
	ds_write_b128 v80, v[104:107]
	v_mfma_f32_32x32x16_bf16 v[32:47], v[132:135], v[116:119], v[32:47]
	v_mfma_f32_32x32x16_bf16 v[16:31], v[132:135], v[120:123], v[16:31]
	ds_read_b128 v[84:87], v74 offset:64
	ds_read_b128 v[104:107], v74 offset:4672
	ds_read_b128 v[116:119], v74 offset:9280
	ds_read_b128 v[120:123], v74 offset:13888
	ds_read_b128 v[124:127], v72 offset:36928
	v_mfma_f32_32x32x16_bf16 v[0:15], v[132:135], v[128:131], v[0:15]
	v_readlane_b32 vcc_lo, v250, 9
	v_readlane_b32 vcc_hi, v250, 10
	s_waitcnt lgkmcnt(0)
	v_mfma_f32_32x32x16_bf16 v[48:63], v[124:127], v[84:87], v[48:63]
	s_waitcnt vmcnt(5)
	ds_write_b128 v81, v[92:95]
	s_nop 0
	global_load_dwordx4 v[84:87], v66, vcc
	v_mfma_f32_32x32x16_bf16 v[32:47], v[124:127], v[104:107], v[32:47]
	v_mfma_f32_32x32x16_bf16 v[16:31], v[124:127], v[116:119], v[16:31]
	ds_read_b128 v[92:95], v74 offset:96
	ds_read_b128 v[104:107], v74 offset:4704
	ds_read_b128 v[116:119], v74 offset:9312
	ds_read_b128 v[128:131], v74 offset:13920
	ds_read_b128 v[132:135], v72 offset:36960
	v_mfma_f32_32x32x16_bf16 v[0:15], v[124:127], v[120:123], v[0:15]
	v_readlane_b32 vcc_lo, v250, 11
	v_readlane_b32 vcc_hi, v250, 12
	s_waitcnt lgkmcnt(0)
	v_mfma_f32_32x32x16_bf16 v[48:63], v[132:135], v[92:95], v[48:63]
	s_waitcnt vmcnt(5)
	ds_write_b128 v82, v[96:99]
	s_nop 0
	global_load_dwordx4 v[92:95], v66, vcc
	v_mfma_f32_32x32x16_bf16 v[32:47], v[132:135], v[104:107], v[32:47]
	v_mfma_f32_32x32x16_bf16 v[16:31], v[132:135], v[116:119], v[16:31]
	v_mfma_f32_32x32x16_bf16 v[0:15], v[132:135], v[128:131], v[0:15]
	s_waitcnt lgkmcnt(0)
	s_barrier
; #define H_MMA(F) { _Pragma("unroll") for (int mb = 0; mb < 4; ++mb) acc[mb] = __builtin_amdgcn_mfma_f32_32x32x16_bf16(F[4], F[mb], acc[mb], 0, 0, 0); }
; DI void gemm_half_rowbf16(const bf16_t* __restrict__ A, int lda, const bf16_t* __restrict__ Bt, int ldb, int K, int m0, int n0, char* smem, bf16_t* __restrict__ Out, int ldo) {
;     ...
;   const int nk = K / 64;
;   H_LOADA(0, 0); H_LOADA(1, 0); H_LOADB(0, 0); H_LOADB(1, 0); H_LOADB(2, 0); H_LOADB(3, 0);
;   H_STOREA(0, 0); H_STOREA(0, 1); H_STOREB(0, 0); H_STOREB(0, 1); H_STOREB(0, 2); H_STOREB(0, 3);
;   if (nk > 1) { H_LOADA(0, 1); H_LOADA(1, 1); H_LOADB(0, 1); H_LOADB(1, 1); H_LOADB(2, 1); H_LOADB(3, 1); }
;   for (int kt = 0; kt < nk; ++kt) {
;     const int st = kt & 1;
;     __syncthreads();
;     bf16x8 f0[5], f1[5];
;     H_FRAGS(f0, st, 0);
;     H_PART(0, st, kt); H_FRAGS(f1, st, 1); H_MMA(f0); __builtin_amdgcn_sched_barrier(0);
;     H_PART(1, st, kt); H_FRAGS(f0, st, 2); H_MMA(f1); __builtin_amdgcn_sched_barrier(0);
;     H_PART(2, st, kt); H_FRAGS(f1, st, 3); H_MMA(f0); __builtin_amdgcn_sched_barrier(0);
;     H_PART(3, st, kt); H_MMA(f1); __builtin_amdgcn_sched_barrier(0);
;   }
	ds_read_b128 v[96:99], v75
	ds_read_b128 v[104:107], v76
	ds_read_b128 v[116:119], v76 offset:4608
	s_waitcnt lgkmcnt(1)
	v_mfma_f32_32x32x16_bf16 v[48:63], v[96:99], v[104:107], v[48:63]
	s_waitcnt lgkmcnt(0)
	v_mfma_f32_32x32x16_bf16 v[32:47], v[96:99], v[116:119], v[32:47]
	global_load_dwordx4 v[104:107], v66, s[4:5] offset:1664
	global_load_dwordx4 v[116:119], v66, s[34:35] offset:1664
	ds_read_b128 v[120:123], v76 offset:9216
	ds_read_b128 v[124:127], v76 offset:13824
	s_waitcnt vmcnt(7)
	ds_write_b128 v73, v[108:111] offset:36864
	s_waitcnt vmcnt(6)
	ds_write_b128 v73, v[112:115]
	s_waitcnt lgkmcnt(3)
	v_mfma_f32_32x32x16_bf16 v[16:31], v[96:99], v[120:123], v[16:31]
	ds_read_b128 v[108:111], v76 offset:32
	ds_read_b128 v[112:115], v76 offset:4640
	ds_read_b128 v[120:123], v76 offset:9248
	ds_read_b128 v[128:131], v76 offset:13856
	ds_read_b128 v[132:135], v75 offset:32
	s_waitcnt lgkmcnt(7)
	v_mfma_f32_32x32x16_bf16 v[0:15], v[96:99], v[124:127], v[0:15]
	v_readlane_b32 vcc_lo, v250, 13
	v_readlane_b32 vcc_hi, v250, 14
	s_waitcnt lgkmcnt(0)
	v_mfma_f32_32x32x16_bf16 v[48:63], v[132:135], v[108:111], v[48:63]
	global_load_dwordx4 v[108:111], v[68:69], off offset:1664
	s_nop 1
	global_load_dwordx4 v[96:99], v66, vcc
	s_waitcnt vmcnt(6)
	ds_write_b128 v73, v[88:91] offset:46080
	ds_write_b128 v73, v[100:103] offset:9216
	v_mfma_f32_32x32x16_bf16 v[32:47], v[132:135], v[112:115], v[32:47]
	v_mfma_f32_32x32x16_bf16 v[16:31], v[132:135], v[120:123], v[16:31]
	ds_read_b128 v[88:91], v76 offset:64
	ds_read_b128 v[100:103], v76 offset:4672
	ds_read_b128 v[112:115], v76 offset:9280
	ds_read_b128 v[120:123], v76 offset:13888
	ds_read_b128 v[124:127], v75 offset:64
	v_mfma_f32_32x32x16_bf16 v[0:15], v[132:135], v[128:131], v[0:15]
	v_readlane_b32 vcc_lo, v250, 15
	v_readlane_b32 vcc_hi, v250, 16
	s_waitcnt lgkmcnt(0)
	v_mfma_f32_32x32x16_bf16 v[48:63], v[124:127], v[88:91], v[48:63]
	s_waitcnt vmcnt(5)
	ds_write_b128 v73, v[84:87] offset:55296
	s_nop 0
	global_load_dwordx4 v[88:91], v66, vcc
	v_mfma_f32_32x32x16_bf16 v[32:47], v[124:127], v[100:103], v[32:47]
	v_mfma_f32_32x32x16_bf16 v[16:31], v[124:127], v[112:115], v[16:31]
	ds_read_b128 v[84:87], v76 offset:96
	ds_read_b128 v[100:103], v76 offset:4704
	ds_read_b128 v[112:115], v76 offset:9312
	ds_read_b128 v[128:131], v76 offset:13920
	ds_read_b128 v[132:135], v75 offset:96
	v_mfma_f32_32x32x16_bf16 v[0:15], v[124:127], v[120:123], v[0:15]
	v_readlane_b32 vcc_lo, v250, 17
	v_readlane_b32 vcc_hi, v250, 18
	s_waitcnt lgkmcnt(0)
	v_mfma_f32_32x32x16_bf16 v[48:63], v[132:135], v[84:87], v[48:63]
	s_waitcnt vmcnt(5)
	ds_write_b128 v73, v[92:95] offset:64512
	s_nop 0
	global_load_dwordx4 v[84:87], v66, vcc
	v_mfma_f32_32x32x16_bf16 v[32:47], v[132:135], v[100:103], v[32:47]
	v_mfma_f32_32x32x16_bf16 v[16:31], v[132:135], v[112:115], v[16:31]
	v_mfma_f32_32x32x16_bf16 v[0:15], v[132:135], v[128:131], v[0:15]
	s_waitcnt lgkmcnt(0)
	s_barrier
	ds_read_b128 v[92:95], v72 offset:36864
	ds_read_b128 v[100:103], v74
	ds_read_b128 v[112:115], v74 offset:4608
	s_waitcnt lgkmcnt(1)
	v_mfma_f32_32x32x16_bf16 v[48:63], v[92:95], v[100:103], v[48:63]
	s_waitcnt lgkmcnt(0)
	v_mfma_f32_32x32x16_bf16 v[32:47], v[92:95], v[112:115], v[32:47]
	global_load_dwordx4 v[100:103], v66, s[4:5] offset:1792
	global_load_dwordx4 v[112:115], v66, s[34:35] offset:1792
	ds_read_b128 v[120:123], v74 offset:9216
	ds_read_b128 v[124:127], v74 offset:13824
	s_waitcnt vmcnt(7)
	ds_write_b128 v77, v[104:107]
	s_waitcnt vmcnt(6)
	ds_write_b128 v78, v[116:119]
	s_waitcnt lgkmcnt(3)
	v_mfma_f32_32x32x16_bf16 v[16:31], v[92:95], v[120:123], v[16:31]
	ds_read_b128 v[104:107], v74 offset:32
	ds_read_b128 v[116:119], v74 offset:4640
	ds_read_b128 v[120:123], v74 offset:9248
	ds_read_b128 v[128:131], v74 offset:13856
	ds_read_b128 v[132:135], v72 offset:36896
	s_waitcnt lgkmcnt(7)
	v_mfma_f32_32x32x16_bf16 v[0:15], v[92:95], v[124:127], v[0:15]
	v_readlane_b32 vcc_lo, v250, 19
	v_readlane_b32 vcc_hi, v250, 20
	s_waitcnt lgkmcnt(0)
	v_mfma_f32_32x32x16_bf16 v[48:63], v[132:135], v[104:107], v[48:63]
	global_load_dwordx4 v[104:107], v[68:69], off offset:1792
	s_nop 1
	global_load_dwordx4 v[92:95], v66, vcc
	s_waitcnt vmcnt(6)
	ds_write_b128 v79, v[96:99]
	ds_write_b128 v80, v[108:111]
	v_mfma_f32_32x32x16_bf16 v[32:47], v[132:135], v[116:119], v[32:47]
	v_mfma_f32_32x32x16_bf16 v[16:31], v[132:135], v[120:123], v[16:31]
	ds_read_b128 v[96:99], v74 offset:64
	ds_read_b128 v[108:111], v74 offset:4672
	ds_read_b128 v[116:119], v74 offset:9280
	ds_read_b128 v[120:123], v74 offset:13888
	ds_read_b128 v[124:127], v72 offset:36928
	v_mfma_f32_32x32x16_bf16 v[0:15], v[132:135], v[128:131], v[0:15]
	v_readlane_b32 vcc_lo, v250, 21
	v_readlane_b32 vcc_hi, v250, 22
	s_waitcnt lgkmcnt(0)
	v_mfma_f32_32x32x16_bf16 v[48:63], v[124:127], v[96:99], v[48:63]
	s_waitcnt vmcnt(5)
	ds_write_b128 v81, v[88:91]
	s_nop 0
	global_load_dwordx4 v[96:99], v66, vcc
	v_mfma_f32_32x32x16_bf16 v[32:47], v[124:127], v[108:111], v[32:47]
	v_mfma_f32_32x32x16_bf16 v[16:31], v[124:127], v[116:119], v[16:31]
	ds_read_b128 v[88:91], v74 offset:96
	ds_read_b128 v[108:111], v74 offset:4704
	ds_read_b128 v[116:119], v74 offset:9312
	ds_read_b128 v[128:131], v74 offset:13920
	ds_read_b128 v[132:135], v72 offset:36960
	v_mfma_f32_32x32x16_bf16 v[0:15], v[124:127], v[120:123], v[0:15]
	v_readlane_b32 vcc_lo, v250, 23
	v_readlane_b32 vcc_hi, v250, 24
	s_waitcnt lgkmcnt(0)
	v_mfma_f32_32x32x16_bf16 v[48:63], v[132:135], v[88:91], v[48:63]
	s_waitcnt vmcnt(5)
	ds_write_b128 v82, v[84:87]
	s_nop 0
	global_load_dwordx4 v[88:91], v66, vcc
	v_mfma_f32_32x32x16_bf16 v[32:47], v[132:135], v[108:111], v[32:47]
	v_mfma_f32_32x32x16_bf16 v[16:31], v[132:135], v[116:119], v[16:31]
	v_mfma_f32_32x32x16_bf16 v[0:15], v[132:135], v[128:131], v[0:15]
	s_waitcnt lgkmcnt(0)
	s_barrier
; #define H_MMA(F) { _Pragma("unroll") for (int mb = 0; mb < 4; ++mb) acc[mb] = __builtin_amdgcn_mfma_f32_32x32x16_bf16(F[4], F[mb], acc[mb], 0, 0, 0); }
; DI void gemm_half_rowbf16(const bf16_t* __restrict__ A, int lda, const bf16_t* __restrict__ Bt, int ldb, int K, int m0, int n0, char* smem, bf16_t* __restrict__ Out, int ldo) {
;     ...
;   const int nk = K / 64;
;   H_LOADA(0, 0); H_LOADA(1, 0); H_LOADB(0, 0); H_LOADB(1, 0); H_LOADB(2, 0); H_LOADB(3, 0);
;   H_STOREA(0, 0); H_STOREA(0, 1); H_STOREB(0, 0); H_STOREB(0, 1); H_STOREB(0, 2); H_STOREB(0, 3);
;   if (nk > 1) { H_LOADA(0, 1); H_LOADA(1, 1); H_LOADB(0, 1); H_LOADB(1, 1); H_LOADB(2, 1); H_LOADB(3, 1); }
;   for (int kt = 0; kt < nk; ++kt) {
;     const int st = kt & 1;
;     __syncthreads();
;     bf16x8 f0[5], f1[5];
;     H_FRAGS(f0, st, 0);
;     H_PART(0, st, kt); H_FRAGS(f1, st, 1); H_MMA(f0); __builtin_amdgcn_sched_barrier(0);
;     H_PART(1, st, kt); H_FRAGS(f0, st, 2); H_MMA(f1); __builtin_amdgcn_sched_barrier(0);
;     H_PART(2, st, kt); H_FRAGS(f1, st, 3); H_MMA(f0); __builtin_amdgcn_sched_barrier(0);
;     H_PART(3, st, kt); H_MMA(f1); __builtin_amdgcn_sched_barrier(0);
;   }
	ds_read_b128 v[84:87], v75
	ds_read_b128 v[108:111], v76
	ds_read_b128 v[116:119], v76 offset:4608
	s_waitcnt lgkmcnt(1)
	v_mfma_f32_32x32x16_bf16 v[48:63], v[84:87], v[108:111], v[48:63]
	s_waitcnt lgkmcnt(0)
	v_mfma_f32_32x32x16_bf16 v[32:47], v[84:87], v[116:119], v[32:47]
	global_load_dwordx4 v[108:111], v66, s[4:5] offset:1920
	global_load_dwordx4 v[116:119], v66, s[34:35] offset:1920
	ds_read_b128 v[120:123], v76 offset:9216
	ds_read_b128 v[124:127], v76 offset:13824
	s_waitcnt vmcnt(7)
	ds_write_b128 v73, v[100:103] offset:36864
	s_waitcnt vmcnt(6)
	ds_write_b128 v73, v[112:115]
	s_waitcnt lgkmcnt(3)
	v_mfma_f32_32x32x16_bf16 v[16:31], v[84:87], v[120:123], v[16:31]
	ds_read_b128 v[100:103], v76 offset:32
	ds_read_b128 v[112:115], v76 offset:4640
	ds_read_b128 v[120:123], v76 offset:9248
	ds_read_b128 v[128:131], v76 offset:13856
	ds_read_b128 v[132:135], v75 offset:32
	s_waitcnt lgkmcnt(7)
	v_mfma_f32_32x32x16_bf16 v[0:15], v[84:87], v[124:127], v[0:15]
	v_readlane_b32 vcc_lo, v250, 25
	v_readlane_b32 vcc_hi, v250, 26
	s_waitcnt lgkmcnt(0)
	v_mfma_f32_32x32x16_bf16 v[48:63], v[132:135], v[100:103], v[48:63]
	global_load_dwordx4 v[100:103], v[68:69], off offset:1920
	s_nop 1
	global_load_dwordx4 v[84:87], v66, vcc
	s_waitcnt vmcnt(6)
	ds_write_b128 v73, v[92:95] offset:46080
	ds_write_b128 v73, v[104:107] offset:9216
	v_mfma_f32_32x32x16_bf16 v[32:47], v[132:135], v[112:115], v[32:47]
	v_mfma_f32_32x32x16_bf16 v[16:31], v[132:135], v[120:123], v[16:31]
	ds_read_b128 v[92:95], v76 offset:64
	ds_read_b128 v[104:107], v76 offset:4672
	ds_read_b128 v[112:115], v76 offset:9280
	ds_read_b128 v[120:123], v76 offset:13888
	ds_read_b128 v[124:127], v75 offset:64
	v_mfma_f32_32x32x16_bf16 v[0:15], v[132:135], v[128:131], v[0:15]
	v_readlane_b32 vcc_lo, v250, 27
	v_readlane_b32 vcc_hi, v250, 28
	s_waitcnt lgkmcnt(0)
	v_mfma_f32_32x32x16_bf16 v[48:63], v[124:127], v[92:95], v[48:63]
	s_waitcnt vmcnt(5)
	ds_write_b128 v73, v[96:99] offset:55296
	s_nop 0
	global_load_dwordx4 v[92:95], v66, vcc
	v_mfma_f32_32x32x16_bf16 v[32:47], v[124:127], v[104:107], v[32:47]
	v_mfma_f32_32x32x16_bf16 v[16:31], v[124:127], v[112:115], v[16:31]
	ds_read_b128 v[96:99], v76 offset:96
	ds_read_b128 v[104:107], v76 offset:4704
	ds_read_b128 v[112:115], v76 offset:9312
	ds_read_b128 v[128:131], v76 offset:13920
	ds_read_b128 v[132:135], v75 offset:96
	v_mfma_f32_32x32x16_bf16 v[0:15], v[124:127], v[120:123], v[0:15]
	v_readlane_b32 vcc_lo, v250, 29
	v_readlane_b32 vcc_hi, v250, 30
	s_waitcnt lgkmcnt(0)
	v_mfma_f32_32x32x16_bf16 v[48:63], v[132:135], v[96:99], v[48:63]
	s_waitcnt vmcnt(5)
	ds_write_b128 v73, v[88:91] offset:64512
	s_nop 0
	global_load_dwordx4 v[96:99], v66, vcc
	v_mfma_f32_32x32x16_bf16 v[32:47], v[132:135], v[104:107], v[32:47]
	v_mfma_f32_32x32x16_bf16 v[16:31], v[132:135], v[112:115], v[16:31]
	v_mfma_f32_32x32x16_bf16 v[0:15], v[132:135], v[128:131], v[0:15]
	s_waitcnt lgkmcnt(0)
	s_barrier
	ds_read_b128 v[88:91], v72 offset:36864
	ds_read_b128 v[104:107], v74
	ds_read_b128 v[112:115], v74 offset:4608
	s_waitcnt lgkmcnt(1)
	v_mfma_f32_32x32x16_bf16 v[48:63], v[88:91], v[104:107], v[48:63]
	s_waitcnt lgkmcnt(0)
	v_mfma_f32_32x32x16_bf16 v[32:47], v[88:91], v[112:115], v[32:47]
	global_load_dwordx4 v[104:107], v66, s[4:5] offset:2048
	global_load_dwordx4 v[112:115], v66, s[34:35] offset:2048
	ds_read_b128 v[120:123], v74 offset:9216
	ds_read_b128 v[124:127], v74 offset:13824
	s_waitcnt vmcnt(7)
	ds_write_b128 v77, v[108:111]
	s_waitcnt vmcnt(6)
	ds_write_b128 v78, v[116:119]
	s_waitcnt lgkmcnt(3)
	v_mfma_f32_32x32x16_bf16 v[16:31], v[88:91], v[120:123], v[16:31]
	ds_read_b128 v[108:111], v74 offset:32
	ds_read_b128 v[116:119], v74 offset:4640
	ds_read_b128 v[120:123], v74 offset:9248
	ds_read_b128 v[128:131], v74 offset:13856
	ds_read_b128 v[132:135], v72 offset:36896
	s_waitcnt lgkmcnt(7)
	v_mfma_f32_32x32x16_bf16 v[0:15], v[88:91], v[124:127], v[0:15]
	v_readlane_b32 vcc_lo, v250, 31
	v_readlane_b32 vcc_hi, v250, 32
	s_waitcnt lgkmcnt(0)
	v_mfma_f32_32x32x16_bf16 v[48:63], v[132:135], v[108:111], v[48:63]
	global_load_dwordx4 v[108:111], v[68:69], off offset:2048
	s_nop 1
	global_load_dwordx4 v[88:91], v66, vcc
	s_waitcnt vmcnt(6)
	ds_write_b128 v79, v[84:87]
	ds_write_b128 v80, v[100:103]
	v_mfma_f32_32x32x16_bf16 v[32:47], v[132:135], v[116:119], v[32:47]
	v_mfma_f32_32x32x16_bf16 v[16:31], v[132:135], v[120:123], v[16:31]
	ds_read_b128 v[84:87], v74 offset:64
	ds_read_b128 v[100:103], v74 offset:4672
	ds_read_b128 v[116:119], v74 offset:9280
	ds_read_b128 v[120:123], v74 offset:13888
	ds_read_b128 v[124:127], v72 offset:36928
	v_mfma_f32_32x32x16_bf16 v[0:15], v[132:135], v[128:131], v[0:15]
	v_readlane_b32 vcc_lo, v250, 33
	v_readlane_b32 vcc_hi, v250, 34
	s_waitcnt lgkmcnt(0)
	v_mfma_f32_32x32x16_bf16 v[48:63], v[124:127], v[84:87], v[48:63]
	s_waitcnt vmcnt(5)
	ds_write_b128 v81, v[92:95]
	s_nop 0
	global_load_dwordx4 v[84:87], v66, vcc
	v_mfma_f32_32x32x16_bf16 v[32:47], v[124:127], v[100:103], v[32:47]
	v_mfma_f32_32x32x16_bf16 v[16:31], v[124:127], v[116:119], v[16:31]
	ds_read_b128 v[92:95], v74 offset:96
	ds_read_b128 v[100:103], v74 offset:4704
	ds_read_b128 v[116:119], v74 offset:9312
	ds_read_b128 v[128:131], v74 offset:13920
	ds_read_b128 v[132:135], v72 offset:36960
	v_mfma_f32_32x32x16_bf16 v[0:15], v[124:127], v[120:123], v[0:15]
	v_readlane_b32 vcc_lo, v250, 35
	v_readlane_b32 vcc_hi, v250, 36
	s_waitcnt lgkmcnt(0)
	v_mfma_f32_32x32x16_bf16 v[48:63], v[132:135], v[92:95], v[48:63]
	s_waitcnt vmcnt(5)
	ds_write_b128 v82, v[96:99]
	s_nop 0
	global_load_dwordx4 v[92:95], v66, vcc
	v_mfma_f32_32x32x16_bf16 v[32:47], v[132:135], v[100:103], v[32:47]
	v_mfma_f32_32x32x16_bf16 v[16:31], v[132:135], v[116:119], v[16:31]
	v_mfma_f32_32x32x16_bf16 v[0:15], v[132:135], v[128:131], v[0:15]
	s_waitcnt lgkmcnt(0)
	s_barrier
; #define H_MMA(F) { _Pragma("unroll") for (int mb = 0; mb < 4; ++mb) acc[mb] = __builtin_amdgcn_mfma_f32_32x32x16_bf16(F[4], F[mb], acc[mb], 0, 0, 0); }
; DI void gemm_half_rowbf16(const bf16_t* __restrict__ A, int lda, const bf16_t* __restrict__ Bt, int ldb, int K, int m0, int n0, char* smem, bf16_t* __restrict__ Out, int ldo) {
;     ...
;   const int nk = K / 64;
;   H_LOADA(0, 0); H_LOADA(1, 0); H_LOADB(0, 0); H_LOADB(1, 0); H_LOADB(2, 0); H_LOADB(3, 0);
;   H_STOREA(0, 0); H_STOREA(0, 1); H_STOREB(0, 0); H_STOREB(0, 1); H_STOREB(0, 2); H_STOREB(0, 3);
;   if (nk > 1) { H_LOADA(0, 1); H_LOADA(1, 1); H_LOADB(0, 1); H_LOADB(1, 1); H_LOADB(2, 1); H_LOADB(3, 1); }
;   for (int kt = 0; kt < nk; ++kt) {
;     const int st = kt & 1;
;     __syncthreads();
;     bf16x8 f0[5], f1[5];
;     H_FRAGS(f0, st, 0);
;     H_PART(0, st, kt); H_FRAGS(f1, st, 1); H_MMA(f0); __builtin_amdgcn_sched_barrier(0);
;     H_PART(1, st, kt); H_FRAGS(f0, st, 2); H_MMA(f1); __builtin_amdgcn_sched_barrier(0);
;     H_PART(2, st, kt); H_FRAGS(f1, st, 3); H_MMA(f0); __builtin_amdgcn_sched_barrier(0);
;     H_PART(3, st, kt); H_MMA(f1); __builtin_amdgcn_sched_barrier(0);
;   }
	ds_read_b128 v[96:99], v75
	ds_read_b128 v[100:103], v76
	ds_read_b128 v[116:119], v76 offset:4608
	s_waitcnt lgkmcnt(1)
	v_mfma_f32_32x32x16_bf16 v[48:63], v[96:99], v[100:103], v[48:63]
	s_waitcnt lgkmcnt(0)
	v_mfma_f32_32x32x16_bf16 v[32:47], v[96:99], v[116:119], v[32:47]
	global_load_dwordx4 v[100:103], v66, s[4:5] offset:2176
	global_load_dwordx4 v[116:119], v66, s[34:35] offset:2176
	ds_read_b128 v[120:123], v76 offset:9216
	ds_read_b128 v[124:127], v76 offset:13824
	s_waitcnt vmcnt(7)
	ds_write_b128 v73, v[104:107] offset:36864
	s_waitcnt vmcnt(6)
	ds_write_b128 v73, v[112:115]
	s_waitcnt lgkmcnt(3)
	v_mfma_f32_32x32x16_bf16 v[16:31], v[96:99], v[120:123], v[16:31]
	ds_read_b128 v[104:107], v76 offset:32
	ds_read_b128 v[112:115], v76 offset:4640
	ds_read_b128 v[120:123], v76 offset:9248
	ds_read_b128 v[128:131], v76 offset:13856
	ds_read_b128 v[132:135], v75 offset:32
	s_waitcnt lgkmcnt(7)
	v_mfma_f32_32x32x16_bf16 v[0:15], v[96:99], v[124:127], v[0:15]
	v_readlane_b32 vcc_lo, v250, 37
	v_readlane_b32 vcc_hi, v250, 38
	s_waitcnt lgkmcnt(0)
	v_mfma_f32_32x32x16_bf16 v[48:63], v[132:135], v[104:107], v[48:63]
	global_load_dwordx4 v[104:107], v[68:69], off offset:2176
	s_nop 1
	global_load_dwordx4 v[96:99], v66, vcc
	s_waitcnt vmcnt(6)
	ds_write_b128 v73, v[88:91] offset:46080
	ds_write_b128 v73, v[108:111] offset:9216
	v_mfma_f32_32x32x16_bf16 v[32:47], v[132:135], v[112:115], v[32:47]
	v_mfma_f32_32x32x16_bf16 v[16:31], v[132:135], v[120:123], v[16:31]
	ds_read_b128 v[88:91], v76 offset:64
	ds_read_b128 v[108:111], v76 offset:4672
	ds_read_b128 v[112:115], v76 offset:9280
	ds_read_b128 v[120:123], v76 offset:13888
	ds_read_b128 v[124:127], v75 offset:64
	v_mfma_f32_32x32x16_bf16 v[0:15], v[132:135], v[128:131], v[0:15]
	v_readlane_b32 vcc_lo, v250, 39
	v_readlane_b32 vcc_hi, v250, 40
	s_waitcnt lgkmcnt(0)
	v_mfma_f32_32x32x16_bf16 v[48:63], v[124:127], v[88:91], v[48:63]
	s_waitcnt vmcnt(5)
	ds_write_b128 v73, v[84:87] offset:55296
	s_nop 0
	global_load_dwordx4 v[88:91], v66, vcc
	v_mfma_f32_32x32x16_bf16 v[32:47], v[124:127], v[108:111], v[32:47]
	v_mfma_f32_32x32x16_bf16 v[16:31], v[124:127], v[112:115], v[16:31]
	ds_read_b128 v[84:87], v76 offset:96
	ds_read_b128 v[108:111], v76 offset:4704
	ds_read_b128 v[112:115], v76 offset:9312
	ds_read_b128 v[128:131], v76 offset:13920
	ds_read_b128 v[132:135], v75 offset:96
	v_mfma_f32_32x32x16_bf16 v[0:15], v[124:127], v[120:123], v[0:15]
	v_readlane_b32 vcc_lo, v250, 41
	v_readlane_b32 vcc_hi, v250, 42
	s_waitcnt lgkmcnt(0)
	v_mfma_f32_32x32x16_bf16 v[48:63], v[132:135], v[84:87], v[48:63]
	s_waitcnt vmcnt(5)
	ds_write_b128 v73, v[92:95] offset:64512
	s_nop 0
	global_load_dwordx4 v[84:87], v66, vcc
	v_mfma_f32_32x32x16_bf16 v[32:47], v[132:135], v[108:111], v[32:47]
	v_mfma_f32_32x32x16_bf16 v[16:31], v[132:135], v[112:115], v[16:31]
	v_mfma_f32_32x32x16_bf16 v[0:15], v[132:135], v[128:131], v[0:15]
	s_waitcnt lgkmcnt(0)
	s_barrier
	ds_read_b128 v[92:95], v72 offset:36864
	ds_read_b128 v[108:111], v74
	ds_read_b128 v[112:115], v74 offset:4608
	s_waitcnt lgkmcnt(1)
	v_mfma_f32_32x32x16_bf16 v[48:63], v[92:95], v[108:111], v[48:63]
	s_waitcnt lgkmcnt(0)
	v_mfma_f32_32x32x16_bf16 v[32:47], v[92:95], v[112:115], v[32:47]
	global_load_dwordx4 v[108:111], v66, s[4:5] offset:2304
	global_load_dwordx4 v[112:115], v66, s[34:35] offset:2304
	ds_read_b128 v[120:123], v74 offset:9216
	ds_read_b128 v[124:127], v74 offset:13824
	s_waitcnt vmcnt(7)
	ds_write_b128 v77, v[100:103]
	s_waitcnt vmcnt(6)
	ds_write_b128 v78, v[116:119]
	s_waitcnt lgkmcnt(3)
	v_mfma_f32_32x32x16_bf16 v[16:31], v[92:95], v[120:123], v[16:31]
	ds_read_b128 v[100:103], v74 offset:32
	ds_read_b128 v[116:119], v74 offset:4640
	ds_read_b128 v[120:123], v74 offset:9248
	ds_read_b128 v[128:131], v74 offset:13856
	ds_read_b128 v[132:135], v72 offset:36896
	s_waitcnt lgkmcnt(7)
	v_mfma_f32_32x32x16_bf16 v[0:15], v[92:95], v[124:127], v[0:15]
	v_readlane_b32 vcc_lo, v250, 43
	v_readlane_b32 vcc_hi, v250, 44
	s_waitcnt lgkmcnt(0)
	v_mfma_f32_32x32x16_bf16 v[48:63], v[132:135], v[100:103], v[48:63]
	global_load_dwordx4 v[100:103], v[68:69], off offset:2304
	s_nop 1
	global_load_dwordx4 v[92:95], v66, vcc
	s_waitcnt vmcnt(6)
	ds_write_b128 v79, v[96:99]
	ds_write_b128 v80, v[104:107]
	v_mfma_f32_32x32x16_bf16 v[32:47], v[132:135], v[116:119], v[32:47]
	v_mfma_f32_32x32x16_bf16 v[16:31], v[132:135], v[120:123], v[16:31]
	ds_read_b128 v[96:99], v74 offset:64
	ds_read_b128 v[104:107], v74 offset:4672
	ds_read_b128 v[116:119], v74 offset:9280
	ds_read_b128 v[120:123], v74 offset:13888
	ds_read_b128 v[124:127], v72 offset:36928
	v_mfma_f32_32x32x16_bf16 v[0:15], v[132:135], v[128:131], v[0:15]
	v_readlane_b32 vcc_lo, v250, 45
	v_readlane_b32 vcc_hi, v250, 46
	s_waitcnt lgkmcnt(0)
	v_mfma_f32_32x32x16_bf16 v[48:63], v[124:127], v[96:99], v[48:63]
	s_waitcnt vmcnt(5)
	ds_write_b128 v81, v[88:91]
	s_nop 0
	global_load_dwordx4 v[96:99], v66, vcc
	v_mfma_f32_32x32x16_bf16 v[32:47], v[124:127], v[104:107], v[32:47]
	v_mfma_f32_32x32x16_bf16 v[16:31], v[124:127], v[116:119], v[16:31]
	ds_read_b128 v[88:91], v74 offset:96
	ds_read_b128 v[104:107], v74 offset:4704
	ds_read_b128 v[116:119], v74 offset:9312
	ds_read_b128 v[128:131], v74 offset:13920
	ds_read_b128 v[132:135], v72 offset:36960
	v_mfma_f32_32x32x16_bf16 v[0:15], v[124:127], v[120:123], v[0:15]
	v_readlane_b32 s54, v250, 47
	v_readlane_b32 s55, v250, 48
	s_waitcnt lgkmcnt(0)
	v_mfma_f32_32x32x16_bf16 v[48:63], v[132:135], v[88:91], v[48:63]
	s_waitcnt vmcnt(5)
	ds_write_b128 v82, v[84:87]
	s_nop 0
	global_load_dwordx4 v[88:91], v66, s[54:55]
	v_mfma_f32_32x32x16_bf16 v[32:47], v[132:135], v[104:107], v[32:47]
	v_mfma_f32_32x32x16_bf16 v[16:31], v[132:135], v[116:119], v[16:31]
	v_mfma_f32_32x32x16_bf16 v[0:15], v[132:135], v[128:131], v[0:15]
	s_waitcnt lgkmcnt(0)
	s_barrier
; #define H_MMA(F) { _Pragma("unroll") for (int mb = 0; mb < 4; ++mb) acc[mb] = __builtin_amdgcn_mfma_f32_32x32x16_bf16(F[4], F[mb], acc[mb], 0, 0, 0); }
; DI void gemm_half_rowbf16(const bf16_t* __restrict__ A, int lda, const bf16_t* __restrict__ Bt, int ldb, int K, int m0, int n0, char* smem, bf16_t* __restrict__ Out, int ldo) {
;     ...
;   const int nk = K / 64;
;   H_LOADA(0, 0); H_LOADA(1, 0); H_LOADB(0, 0); H_LOADB(1, 0); H_LOADB(2, 0); H_LOADB(3, 0);
;   H_STOREA(0, 0); H_STOREA(0, 1); H_STOREB(0, 0); H_STOREB(0, 1); H_STOREB(0, 2); H_STOREB(0, 3);
;   if (nk > 1) { H_LOADA(0, 1); H_LOADA(1, 1); H_LOADB(0, 1); H_LOADB(1, 1); H_LOADB(2, 1); H_LOADB(3, 1); }
;   for (int kt = 0; kt < nk; ++kt) {
;     const int st = kt & 1;
;     __syncthreads();
;     bf16x8 f0[5], f1[5];
;     H_FRAGS(f0, st, 0);
;     H_PART(0, st, kt); H_FRAGS(f1, st, 1); H_MMA(f0); __builtin_amdgcn_sched_barrier(0);
;     H_PART(1, st, kt); H_FRAGS(f0, st, 2); H_MMA(f1); __builtin_amdgcn_sched_barrier(0);
;     H_PART(2, st, kt); H_FRAGS(f1, st, 3); H_MMA(f0); __builtin_amdgcn_sched_barrier(0);
;     H_PART(3, st, kt); H_MMA(f1); __builtin_amdgcn_sched_barrier(0);
;   }
	ds_read_b128 v[84:87], v75
	ds_read_b128 v[104:107], v76
	ds_read_b128 v[116:119], v76 offset:4608
	s_waitcnt lgkmcnt(1)
	v_mfma_f32_32x32x16_bf16 v[48:63], v[84:87], v[104:107], v[48:63]
	s_waitcnt lgkmcnt(0)
	v_mfma_f32_32x32x16_bf16 v[32:47], v[84:87], v[116:119], v[32:47]
	global_load_dwordx4 v[104:107], v66, s[4:5] offset:2432
	global_load_dwordx4 v[116:119], v66, s[34:35] offset:2432
	ds_read_b128 v[120:123], v76 offset:9216
	ds_read_b128 v[124:127], v76 offset:13824
	s_waitcnt vmcnt(7)
	ds_write_b128 v73, v[108:111] offset:36864
	s_waitcnt vmcnt(6)
	ds_write_b128 v73, v[112:115]
	s_waitcnt lgkmcnt(3)
	v_mfma_f32_32x32x16_bf16 v[16:31], v[84:87], v[120:123], v[16:31]
	ds_read_b128 v[108:111], v76 offset:32
	ds_read_b128 v[112:115], v76 offset:4640
	ds_read_b128 v[120:123], v76 offset:9248
	ds_read_b128 v[128:131], v76 offset:13856
	ds_read_b128 v[132:135], v75 offset:32
	s_waitcnt lgkmcnt(7)
	v_mfma_f32_32x32x16_bf16 v[0:15], v[84:87], v[124:127], v[0:15]
	s_waitcnt lgkmcnt(0)
	v_mfma_f32_32x32x16_bf16 v[48:63], v[132:135], v[108:111], v[48:63]
	global_load_dwordx4 v[84:87], v66, s[66:67]
	global_load_dwordx4 v[108:111], v[68:69], off offset:2432
	s_waitcnt vmcnt(6)
	ds_write_b128 v73, v[92:95] offset:46080
	ds_write_b128 v73, v[100:103] offset:9216
	v_mfma_f32_32x32x16_bf16 v[32:47], v[132:135], v[112:115], v[32:47]
	v_mfma_f32_32x32x16_bf16 v[16:31], v[132:135], v[120:123], v[16:31]
	ds_read_b128 v[92:95], v76 offset:64
	ds_read_b128 v[100:103], v76 offset:4672
	ds_read_b128 v[112:115], v76 offset:9280
	ds_read_b128 v[120:123], v76 offset:13888
	ds_read_b128 v[124:127], v75 offset:64
	v_mfma_f32_32x32x16_bf16 v[0:15], v[132:135], v[128:131], v[0:15]
	s_waitcnt lgkmcnt(0)
	v_mfma_f32_32x32x16_bf16 v[48:63], v[124:127], v[92:95], v[48:63]
	global_load_dwordx4 v[92:95], v66, s[68:69]
	s_waitcnt vmcnt(6)
	ds_write_b128 v73, v[96:99] offset:55296
	v_mfma_f32_32x32x16_bf16 v[32:47], v[124:127], v[100:103], v[32:47]
	v_mfma_f32_32x32x16_bf16 v[16:31], v[124:127], v[112:115], v[16:31]
	ds_read_b128 v[96:99], v76 offset:96
	ds_read_b128 v[100:103], v76 offset:4704
	ds_read_b128 v[112:115], v76 offset:9312
	ds_read_b128 v[128:131], v76 offset:13920
	ds_read_b128 v[132:135], v75 offset:96
	v_mfma_f32_32x32x16_bf16 v[0:15], v[124:127], v[120:123], v[0:15]
	s_waitcnt lgkmcnt(0)
	v_mfma_f32_32x32x16_bf16 v[48:63], v[132:135], v[96:99], v[48:63]
	global_load_dwordx4 v[96:99], v66, s[72:73]
	s_waitcnt vmcnt(6)
	ds_write_b128 v73, v[88:91] offset:64512
	v_mfma_f32_32x32x16_bf16 v[32:47], v[132:135], v[100:103], v[32:47]
	v_mfma_f32_32x32x16_bf16 v[16:31], v[132:135], v[112:115], v[16:31]
	v_mfma_f32_32x32x16_bf16 v[0:15], v[132:135], v[128:131], v[0:15]
	s_waitcnt lgkmcnt(0)
	s_barrier
	ds_read_b128 v[88:91], v72 offset:36864
	ds_read_b128 v[100:103], v74
	ds_read_b128 v[112:115], v74 offset:4608
	s_waitcnt lgkmcnt(1)
	v_mfma_f32_32x32x16_bf16 v[48:63], v[88:91], v[100:103], v[48:63]
	s_waitcnt lgkmcnt(0)
	v_mfma_f32_32x32x16_bf16 v[32:47], v[88:91], v[112:115], v[32:47]
	global_load_dwordx4 v[100:103], v66, s[4:5] offset:2560
	global_load_dwordx4 v[112:115], v66, s[34:35] offset:2560
	ds_read_b128 v[120:123], v74 offset:9216
	ds_read_b128 v[124:127], v74 offset:13824
	s_waitcnt vmcnt(7)
	ds_write_b128 v77, v[104:107]
	s_waitcnt vmcnt(6)
	ds_write_b128 v78, v[116:119]
	s_waitcnt lgkmcnt(3)
	v_mfma_f32_32x32x16_bf16 v[16:31], v[88:91], v[120:123], v[16:31]
	ds_read_b128 v[104:107], v74 offset:32
	ds_read_b128 v[116:119], v74 offset:4640
	ds_read_b128 v[120:123], v74 offset:9248
	ds_read_b128 v[128:131], v74 offset:13856
	ds_read_b128 v[132:135], v72 offset:36896
	s_waitcnt lgkmcnt(7)
	v_mfma_f32_32x32x16_bf16 v[0:15], v[88:91], v[124:127], v[0:15]
	s_waitcnt lgkmcnt(0)
	v_mfma_f32_32x32x16_bf16 v[48:63], v[132:135], v[104:107], v[48:63]
	global_load_dwordx4 v[88:91], v66, s[76:77]
	global_load_dwordx4 v[104:107], v[68:69], off offset:2560
	s_waitcnt vmcnt(7)
	ds_write_b128 v79, v[84:87]
	s_waitcnt vmcnt(6)
	ds_write_b128 v80, v[108:111]
	v_mfma_f32_32x32x16_bf16 v[32:47], v[132:135], v[116:119], v[32:47]
	v_mfma_f32_32x32x16_bf16 v[16:31], v[132:135], v[120:123], v[16:31]
	ds_read_b128 v[84:87], v74 offset:64
	ds_read_b128 v[108:111], v74 offset:4672
	ds_read_b128 v[116:119], v74 offset:9280
	ds_read_b128 v[120:123], v74 offset:13888
	ds_read_b128 v[124:127], v72 offset:36928
	v_mfma_f32_32x32x16_bf16 v[0:15], v[132:135], v[128:131], v[0:15]
	s_waitcnt lgkmcnt(0)
	v_mfma_f32_32x32x16_bf16 v[48:63], v[124:127], v[84:87], v[48:63]
	global_load_dwordx4 v[84:87], v66, s[78:79]
	s_waitcnt vmcnt(6)
	ds_write_b128 v81, v[92:95]
	v_mfma_f32_32x32x16_bf16 v[32:47], v[124:127], v[108:111], v[32:47]
	v_mfma_f32_32x32x16_bf16 v[16:31], v[124:127], v[116:119], v[16:31]
	ds_read_b128 v[92:95], v74 offset:96
	ds_read_b128 v[108:111], v74 offset:4704
	ds_read_b128 v[116:119], v74 offset:9312
	ds_read_b128 v[128:131], v74 offset:13920
	ds_read_b128 v[132:135], v72 offset:36960
	v_mfma_f32_32x32x16_bf16 v[0:15], v[124:127], v[120:123], v[0:15]
	s_waitcnt lgkmcnt(0)
	v_mfma_f32_32x32x16_bf16 v[48:63], v[132:135], v[92:95], v[48:63]
	global_load_dwordx4 v[92:95], v66, s[80:81]
	s_waitcnt vmcnt(6)
	ds_write_b128 v82, v[96:99]
	v_mfma_f32_32x32x16_bf16 v[32:47], v[132:135], v[108:111], v[32:47]
	v_mfma_f32_32x32x16_bf16 v[16:31], v[132:135], v[116:119], v[16:31]
	v_mfma_f32_32x32x16_bf16 v[0:15], v[132:135], v[128:131], v[0:15]
	s_waitcnt lgkmcnt(0)
	s_barrier
; #define H_MMA(F) { _Pragma("unroll") for (int mb = 0; mb < 4; ++mb) acc[mb] = __builtin_amdgcn_mfma_f32_32x32x16_bf16(F[4], F[mb], acc[mb], 0, 0, 0); }
; DI void gemm_half_rowbf16(const bf16_t* __restrict__ A, int lda, const bf16_t* __restrict__ Bt, int ldb, int K, int m0, int n0, char* smem, bf16_t* __restrict__ Out, int ldo) {
;     ...
;   const int nk = K / 64;
;   H_LOADA(0, 0); H_LOADA(1, 0); H_LOADB(0, 0); H_LOADB(1, 0); H_LOADB(2, 0); H_LOADB(3, 0);
;   H_STOREA(0, 0); H_STOREA(0, 1); H_STOREB(0, 0); H_STOREB(0, 1); H_STOREB(0, 2); H_STOREB(0, 3);
;   if (nk > 1) { H_LOADA(0, 1); H_LOADA(1, 1); H_LOADB(0, 1); H_LOADB(1, 1); H_LOADB(2, 1); H_LOADB(3, 1); }
;   for (int kt = 0; kt < nk; ++kt) {
;     const int st = kt & 1;
;     __syncthreads();
;     bf16x8 f0[5], f1[5];
;     H_FRAGS(f0, st, 0);
;     H_PART(0, st, kt); H_FRAGS(f1, st, 1); H_MMA(f0); __builtin_amdgcn_sched_barrier(0);
;     H_PART(1, st, kt); H_FRAGS(f0, st, 2); H_MMA(f1); __builtin_amdgcn_sched_barrier(0);
;     H_PART(2, st, kt); H_FRAGS(f1, st, 3); H_MMA(f0); __builtin_amdgcn_sched_barrier(0);
;     H_PART(3, st, kt); H_MMA(f1); __builtin_amdgcn_sched_barrier(0);
;   }
	ds_read_b128 v[96:99], v75
	ds_read_b128 v[108:111], v76
	ds_read_b128 v[116:119], v76 offset:4608
	s_waitcnt lgkmcnt(1)
	v_mfma_f32_32x32x16_bf16 v[48:63], v[96:99], v[108:111], v[48:63]
	s_waitcnt lgkmcnt(0)
	v_mfma_f32_32x32x16_bf16 v[32:47], v[96:99], v[116:119], v[32:47]
	global_load_dwordx4 v[108:111], v66, s[4:5] offset:2688
	global_load_dwordx4 v[116:119], v66, s[34:35] offset:2688
	ds_read_b128 v[120:123], v76 offset:9216
	ds_read_b128 v[124:127], v76 offset:13824
	s_waitcnt vmcnt(7)
	ds_write_b128 v73, v[100:103] offset:36864
	s_waitcnt vmcnt(6)
	ds_write_b128 v73, v[112:115]
	s_waitcnt lgkmcnt(3)
	v_mfma_f32_32x32x16_bf16 v[16:31], v[96:99], v[120:123], v[16:31]
	ds_read_b128 v[100:103], v76 offset:32
	ds_read_b128 v[112:115], v76 offset:4640
	ds_read_b128 v[120:123], v76 offset:9248
	ds_read_b128 v[128:131], v76 offset:13856
	ds_read_b128 v[132:135], v75 offset:32
	s_waitcnt lgkmcnt(7)
	v_mfma_f32_32x32x16_bf16 v[0:15], v[96:99], v[124:127], v[0:15]
	s_waitcnt lgkmcnt(0)
	v_mfma_f32_32x32x16_bf16 v[48:63], v[132:135], v[100:103], v[48:63]
	global_load_dwordx4 v[96:99], v66, s[82:83]
	global_load_dwordx4 v[100:103], v[68:69], off offset:2688
	s_waitcnt vmcnt(7)
	ds_write_b128 v73, v[88:91] offset:46080
	s_waitcnt vmcnt(6)
	ds_write_b128 v73, v[104:107] offset:9216
	v_mfma_f32_32x32x16_bf16 v[32:47], v[132:135], v[112:115], v[32:47]
	v_mfma_f32_32x32x16_bf16 v[16:31], v[132:135], v[120:123], v[16:31]
	ds_read_b128 v[88:91], v76 offset:64
	ds_read_b128 v[104:107], v76 offset:4672
	ds_read_b128 v[112:115], v76 offset:9280
	ds_read_b128 v[120:123], v76 offset:13888
	ds_read_b128 v[124:127], v75 offset:64
	v_mfma_f32_32x32x16_bf16 v[0:15], v[132:135], v[128:131], v[0:15]
	s_waitcnt lgkmcnt(0)
	v_mfma_f32_32x32x16_bf16 v[48:63], v[124:127], v[88:91], v[48:63]
	global_load_dwordx4 v[88:91], v66, s[84:85]
	s_waitcnt vmcnt(6)
	ds_write_b128 v73, v[84:87] offset:55296
	v_mfma_f32_32x32x16_bf16 v[32:47], v[124:127], v[104:107], v[32:47]
	v_mfma_f32_32x32x16_bf16 v[16:31], v[124:127], v[112:115], v[16:31]
	ds_read_b128 v[84:87], v76 offset:96
	ds_read_b128 v[104:107], v76 offset:4704
	ds_read_b128 v[112:115], v76 offset:9312
	ds_read_b128 v[128:131], v76 offset:13920
	ds_read_b128 v[132:135], v75 offset:96
	v_mfma_f32_32x32x16_bf16 v[0:15], v[124:127], v[120:123], v[0:15]
	s_waitcnt lgkmcnt(0)
	v_mfma_f32_32x32x16_bf16 v[48:63], v[132:135], v[84:87], v[48:63]
	global_load_dwordx4 v[84:87], v66, s[86:87]
	s_waitcnt vmcnt(6)
	ds_write_b128 v73, v[92:95] offset:64512
	v_mfma_f32_32x32x16_bf16 v[32:47], v[132:135], v[104:107], v[32:47]
	v_mfma_f32_32x32x16_bf16 v[16:31], v[132:135], v[112:115], v[16:31]
	v_mfma_f32_32x32x16_bf16 v[0:15], v[132:135], v[128:131], v[0:15]
	s_waitcnt lgkmcnt(0)
	s_barrier
	ds_read_b128 v[92:95], v72 offset:36864
	ds_read_b128 v[104:107], v74
	ds_read_b128 v[112:115], v74 offset:4608
	s_waitcnt lgkmcnt(1)
	v_mfma_f32_32x32x16_bf16 v[48:63], v[92:95], v[104:107], v[48:63]
	s_waitcnt lgkmcnt(0)
	v_mfma_f32_32x32x16_bf16 v[32:47], v[92:95], v[112:115], v[32:47]
	global_load_dwordx4 v[104:107], v66, s[4:5] offset:2816
	global_load_dwordx4 v[112:115], v66, s[34:35] offset:2816
	ds_read_b128 v[120:123], v74 offset:9216
	ds_read_b128 v[124:127], v74 offset:13824
	s_waitcnt vmcnt(7)
	ds_write_b128 v77, v[108:111]
	s_waitcnt vmcnt(6)
	ds_write_b128 v78, v[116:119]
	s_waitcnt lgkmcnt(3)
	v_mfma_f32_32x32x16_bf16 v[16:31], v[92:95], v[120:123], v[16:31]
	ds_read_b128 v[108:111], v74 offset:32
	ds_read_b128 v[116:119], v74 offset:4640
	ds_read_b128 v[120:123], v74 offset:9248
	ds_read_b128 v[128:131], v74 offset:13856
	ds_read_b128 v[132:135], v72 offset:36896
	s_waitcnt lgkmcnt(7)
	v_mfma_f32_32x32x16_bf16 v[0:15], v[92:95], v[124:127], v[0:15]
	s_waitcnt lgkmcnt(0)
	v_mfma_f32_32x32x16_bf16 v[48:63], v[132:135], v[108:111], v[48:63]
	global_load_dwordx4 v[92:95], v66, s[88:89]
	global_load_dwordx4 v[108:111], v[68:69], off offset:2816
	s_waitcnt vmcnt(7)
	ds_write_b128 v79, v[96:99]
	s_waitcnt vmcnt(6)
	ds_write_b128 v80, v[100:103]
	v_mfma_f32_32x32x16_bf16 v[32:47], v[132:135], v[116:119], v[32:47]
	v_mfma_f32_32x32x16_bf16 v[16:31], v[132:135], v[120:123], v[16:31]
	ds_read_b128 v[96:99], v74 offset:64
	ds_read_b128 v[100:103], v74 offset:4672
	ds_read_b128 v[116:119], v74 offset:9280
	ds_read_b128 v[120:123], v74 offset:13888
	ds_read_b128 v[124:127], v72 offset:36928
	v_mfma_f32_32x32x16_bf16 v[0:15], v[132:135], v[128:131], v[0:15]
	s_waitcnt lgkmcnt(0)
	v_mfma_f32_32x32x16_bf16 v[48:63], v[124:127], v[96:99], v[48:63]
	global_load_dwordx4 v[96:99], v66, s[90:91]
	s_waitcnt vmcnt(6)
	ds_write_b128 v81, v[88:91]
	v_mfma_f32_32x32x16_bf16 v[32:47], v[124:127], v[100:103], v[32:47]
	v_mfma_f32_32x32x16_bf16 v[16:31], v[124:127], v[116:119], v[16:31]
	ds_read_b128 v[88:91], v74 offset:96
	ds_read_b128 v[100:103], v74 offset:4704
	ds_read_b128 v[116:119], v74 offset:9312
	ds_read_b128 v[128:131], v74 offset:13920
	ds_read_b128 v[132:135], v72 offset:36960
	v_mfma_f32_32x32x16_bf16 v[0:15], v[124:127], v[120:123], v[0:15]
	s_waitcnt lgkmcnt(0)
	v_mfma_f32_32x32x16_bf16 v[48:63], v[132:135], v[88:91], v[48:63]
	global_load_dwordx4 v[88:91], v66, s[92:93]
	s_waitcnt vmcnt(6)
	ds_write_b128 v82, v[84:87]
	v_mfma_f32_32x32x16_bf16 v[32:47], v[132:135], v[100:103], v[32:47]
	v_mfma_f32_32x32x16_bf16 v[16:31], v[132:135], v[116:119], v[16:31]
	v_mfma_f32_32x32x16_bf16 v[0:15], v[132:135], v[128:131], v[0:15]
	s_waitcnt lgkmcnt(0)
	s_barrier
; #define H_MMA(F) { _Pragma("unroll") for (int mb = 0; mb < 4; ++mb) acc[mb] = __builtin_amdgcn_mfma_f32_32x32x16_bf16(F[4], F[mb], acc[mb], 0, 0, 0); }
; DI void gemm_half_rowbf16(const bf16_t* __restrict__ A, int lda, const bf16_t* __restrict__ Bt, int ldb, int K, int m0, int n0, char* smem, bf16_t* __restrict__ Out, int ldo) {
;     ...
;   const int nk = K / 64;
;   H_LOADA(0, 0); H_LOADA(1, 0); H_LOADB(0, 0); H_LOADB(1, 0); H_LOADB(2, 0); H_LOADB(3, 0);
;   H_STOREA(0, 0); H_STOREA(0, 1); H_STOREB(0, 0); H_STOREB(0, 1); H_STOREB(0, 2); H_STOREB(0, 3);
;   if (nk > 1) { H_LOADA(0, 1); H_LOADA(1, 1); H_LOADB(0, 1); H_LOADB(1, 1); H_LOADB(2, 1); H_LOADB(3, 1); }
;   for (int kt = 0; kt < nk; ++kt) {
;     const int st = kt & 1;
;     __syncthreads();
;     bf16x8 f0[5], f1[5];
;     H_FRAGS(f0, st, 0);
;     H_PART(0, st, kt); H_FRAGS(f1, st, 1); H_MMA(f0); __builtin_amdgcn_sched_barrier(0);
;     H_PART(1, st, kt); H_FRAGS(f0, st, 2); H_MMA(f1); __builtin_amdgcn_sched_barrier(0);
;     H_PART(2, st, kt); H_FRAGS(f1, st, 3); H_MMA(f0); __builtin_amdgcn_sched_barrier(0);
;     H_PART(3, st, kt); H_MMA(f1); __builtin_amdgcn_sched_barrier(0);
;   }
	ds_read_b128 v[84:87], v75
	ds_read_b128 v[100:103], v76
	ds_read_b128 v[116:119], v76 offset:4608
	s_waitcnt lgkmcnt(1)
	v_mfma_f32_32x32x16_bf16 v[48:63], v[84:87], v[100:103], v[48:63]
	s_waitcnt lgkmcnt(0)
	v_mfma_f32_32x32x16_bf16 v[32:47], v[84:87], v[116:119], v[32:47]
	global_load_dwordx4 v[100:103], v66, s[4:5] offset:2944
	global_load_dwordx4 v[116:119], v66, s[34:35] offset:2944
	ds_read_b128 v[120:123], v76 offset:9216
	ds_read_b128 v[124:127], v76 offset:13824
	s_waitcnt vmcnt(7)
	ds_write_b128 v73, v[104:107] offset:36864
	s_waitcnt vmcnt(6)
	ds_write_b128 v73, v[112:115]
	s_waitcnt lgkmcnt(3)
	v_mfma_f32_32x32x16_bf16 v[16:31], v[84:87], v[120:123], v[16:31]
	ds_read_b128 v[104:107], v76 offset:32
	ds_read_b128 v[112:115], v76 offset:4640
	ds_read_b128 v[120:123], v76 offset:9248
	ds_read_b128 v[128:131], v76 offset:13856
	ds_read_b128 v[132:135], v75 offset:32
	s_waitcnt lgkmcnt(7)
	v_mfma_f32_32x32x16_bf16 v[0:15], v[84:87], v[124:127], v[0:15]
	s_waitcnt lgkmcnt(0)
	v_mfma_f32_32x32x16_bf16 v[48:63], v[132:135], v[104:107], v[48:63]
	global_load_dwordx4 v[84:87], v66, s[94:95]
	global_load_dwordx4 v[104:107], v[68:69], off offset:2944
	s_waitcnt vmcnt(7)
	ds_write_b128 v73, v[92:95] offset:46080
	s_waitcnt vmcnt(6)
	ds_write_b128 v73, v[108:111] offset:9216
	v_mfma_f32_32x32x16_bf16 v[32:47], v[132:135], v[112:115], v[32:47]
	v_mfma_f32_32x32x16_bf16 v[16:31], v[132:135], v[120:123], v[16:31]
	ds_read_b128 v[92:95], v76 offset:64
	ds_read_b128 v[108:111], v76 offset:4672
	ds_read_b128 v[112:115], v76 offset:9280
	ds_read_b128 v[120:123], v76 offset:13888
	ds_read_b128 v[124:127], v75 offset:64
	v_mfma_f32_32x32x16_bf16 v[0:15], v[132:135], v[128:131], v[0:15]
	s_waitcnt lgkmcnt(0)
	v_mfma_f32_32x32x16_bf16 v[48:63], v[124:127], v[92:95], v[48:63]
	global_load_dwordx4 v[92:95], v66, s[52:53]
	s_waitcnt vmcnt(6)
	ds_write_b128 v73, v[96:99] offset:55296
	v_mfma_f32_32x32x16_bf16 v[32:47], v[124:127], v[108:111], v[32:47]
	v_mfma_f32_32x32x16_bf16 v[16:31], v[124:127], v[112:115], v[16:31]
	ds_read_b128 v[96:99], v76 offset:96
	ds_read_b128 v[108:111], v76 offset:4704
	ds_read_b128 v[112:115], v76 offset:9312
	ds_read_b128 v[128:131], v76 offset:13920
	ds_read_b128 v[132:135], v75 offset:96
	v_mfma_f32_32x32x16_bf16 v[0:15], v[124:127], v[120:123], v[0:15]
	s_waitcnt lgkmcnt(0)
	v_mfma_f32_32x32x16_bf16 v[48:63], v[132:135], v[96:99], v[48:63]
	global_load_dwordx4 v[96:99], v66, s[0:1]
	s_waitcnt vmcnt(6)
	ds_write_b128 v73, v[88:91] offset:64512
	v_mfma_f32_32x32x16_bf16 v[32:47], v[132:135], v[108:111], v[32:47]
	v_mfma_f32_32x32x16_bf16 v[16:31], v[132:135], v[112:115], v[16:31]
	v_mfma_f32_32x32x16_bf16 v[0:15], v[132:135], v[128:131], v[0:15]
	s_waitcnt lgkmcnt(0)
	s_barrier
	ds_read_b128 v[88:91], v72 offset:36864
	ds_read_b128 v[108:111], v74
	ds_read_b128 v[112:115], v74 offset:4608
	s_waitcnt lgkmcnt(1)
	v_mfma_f32_32x32x16_bf16 v[48:63], v[88:91], v[108:111], v[48:63]
	s_waitcnt lgkmcnt(0)
	v_mfma_f32_32x32x16_bf16 v[32:47], v[88:91], v[112:115], v[32:47]
	global_load_dwordx4 v[108:111], v66, s[4:5] offset:3072
	global_load_dwordx4 v[112:115], v66, s[34:35] offset:3072
	ds_read_b128 v[120:123], v74 offset:9216
	ds_read_b128 v[124:127], v74 offset:13824
	s_waitcnt vmcnt(7)
	ds_write_b128 v77, v[100:103]
	s_waitcnt vmcnt(6)
	ds_write_b128 v78, v[116:119]
	s_waitcnt lgkmcnt(3)
	v_mfma_f32_32x32x16_bf16 v[16:31], v[88:91], v[120:123], v[16:31]
	ds_read_b128 v[100:103], v74 offset:32
	ds_read_b128 v[116:119], v74 offset:4640
	ds_read_b128 v[120:123], v74 offset:9248
	ds_read_b128 v[128:131], v74 offset:13856
	ds_read_b128 v[132:135], v72 offset:36896
	s_waitcnt lgkmcnt(7)
	v_mfma_f32_32x32x16_bf16 v[0:15], v[88:91], v[124:127], v[0:15]
	s_waitcnt lgkmcnt(0)
	v_mfma_f32_32x32x16_bf16 v[48:63], v[132:135], v[100:103], v[48:63]
	global_load_dwordx4 v[88:91], v66, s[16:17]
	global_load_dwordx4 v[100:103], v[68:69], off offset:3072
	s_waitcnt vmcnt(7)
	ds_write_b128 v79, v[84:87]
	s_waitcnt vmcnt(6)
	ds_write_b128 v80, v[104:107]
	v_mfma_f32_32x32x16_bf16 v[32:47], v[132:135], v[116:119], v[32:47]
	v_mfma_f32_32x32x16_bf16 v[16:31], v[132:135], v[120:123], v[16:31]
	ds_read_b128 v[84:87], v74 offset:64
	ds_read_b128 v[104:107], v74 offset:4672
	ds_read_b128 v[116:119], v74 offset:9280
	ds_read_b128 v[120:123], v74 offset:13888
	ds_read_b128 v[124:127], v72 offset:36928
	v_mfma_f32_32x32x16_bf16 v[0:15], v[132:135], v[128:131], v[0:15]
	s_waitcnt lgkmcnt(0)
	v_mfma_f32_32x32x16_bf16 v[48:63], v[124:127], v[84:87], v[48:63]
	global_load_dwordx4 v[84:87], v66, s[18:19]
	s_waitcnt vmcnt(6)
	ds_write_b128 v81, v[92:95]
	v_mfma_f32_32x32x16_bf16 v[32:47], v[124:127], v[104:107], v[32:47]
	v_mfma_f32_32x32x16_bf16 v[16:31], v[124:127], v[116:119], v[16:31]
	ds_read_b128 v[92:95], v74 offset:96
	ds_read_b128 v[104:107], v74 offset:4704
	ds_read_b128 v[116:119], v74 offset:9312
	ds_read_b128 v[128:131], v74 offset:13920
	ds_read_b128 v[132:135], v72 offset:36960
	v_mfma_f32_32x32x16_bf16 v[0:15], v[124:127], v[120:123], v[0:15]
	s_waitcnt lgkmcnt(0)
	v_mfma_f32_32x32x16_bf16 v[48:63], v[132:135], v[92:95], v[48:63]
	global_load_dwordx4 v[92:95], v66, s[36:37]
	s_waitcnt vmcnt(6)
	ds_write_b128 v82, v[96:99]
	v_mfma_f32_32x32x16_bf16 v[32:47], v[132:135], v[104:107], v[32:47]
	v_mfma_f32_32x32x16_bf16 v[16:31], v[132:135], v[116:119], v[16:31]
	v_mfma_f32_32x32x16_bf16 v[0:15], v[132:135], v[128:131], v[0:15]
	s_waitcnt lgkmcnt(0)
	s_barrier
; #define H_MMA(F) { _Pragma("unroll") for (int mb = 0; mb < 4; ++mb) acc[mb] = __builtin_amdgcn_mfma_f32_32x32x16_bf16(F[4], F[mb], acc[mb], 0, 0, 0); }
; DI void gemm_half_rowbf16(const bf16_t* __restrict__ A, int lda, const bf16_t* __restrict__ Bt, int ldb, int K, int m0, int n0, char* smem, bf16_t* __restrict__ Out, int ldo) {
;     ...
;   const int nk = K / 64;
;   H_LOADA(0, 0); H_LOADA(1, 0); H_LOADB(0, 0); H_LOADB(1, 0); H_LOADB(2, 0); H_LOADB(3, 0);
;   H_STOREA(0, 0); H_STOREA(0, 1); H_STOREB(0, 0); H_STOREB(0, 1); H_STOREB(0, 2); H_STOREB(0, 3);
;   if (nk > 1) { H_LOADA(0, 1); H_LOADA(1, 1); H_LOADB(0, 1); H_LOADB(1, 1); H_LOADB(2, 1); H_LOADB(3, 1); }
;   for (int kt = 0; kt < nk; ++kt) {
;     const int st = kt & 1;
;     __syncthreads();
;     bf16x8 f0[5], f1[5];
;     H_FRAGS(f0, st, 0);
;     H_PART(0, st, kt); H_FRAGS(f1, st, 1); H_MMA(f0); __builtin_amdgcn_sched_barrier(0);
;     H_PART(1, st, kt); H_FRAGS(f0, st, 2); H_MMA(f1); __builtin_amdgcn_sched_barrier(0);
;     H_PART(2, st, kt); H_FRAGS(f1, st, 3); H_MMA(f0); __builtin_amdgcn_sched_barrier(0);
;     H_PART(3, st, kt); H_MMA(f1); __builtin_amdgcn_sched_barrier(0);
;   }
	ds_read_b128 v[96:99], v75
	ds_read_b128 v[104:107], v76
	ds_read_b128 v[116:119], v76 offset:4608
	s_waitcnt lgkmcnt(1)
	v_mfma_f32_32x32x16_bf16 v[48:63], v[96:99], v[104:107], v[48:63]
	s_waitcnt lgkmcnt(0)
	v_mfma_f32_32x32x16_bf16 v[32:47], v[96:99], v[116:119], v[32:47]
	global_load_dwordx4 v[104:107], v66, s[4:5] offset:3200
	global_load_dwordx4 v[116:119], v66, s[34:35] offset:3200
	ds_read_b128 v[120:123], v76 offset:9216
	ds_read_b128 v[124:127], v76 offset:13824
	s_waitcnt vmcnt(7)
	ds_write_b128 v73, v[108:111] offset:36864
	s_waitcnt vmcnt(6)
	ds_write_b128 v73, v[112:115]
	s_waitcnt lgkmcnt(3)
	v_mfma_f32_32x32x16_bf16 v[16:31], v[96:99], v[120:123], v[16:31]
	ds_read_b128 v[108:111], v76 offset:32
	ds_read_b128 v[112:115], v76 offset:4640
	ds_read_b128 v[120:123], v76 offset:9248
	ds_read_b128 v[128:131], v76 offset:13856
	ds_read_b128 v[132:135], v75 offset:32
	s_waitcnt lgkmcnt(7)
	v_mfma_f32_32x32x16_bf16 v[0:15], v[96:99], v[124:127], v[0:15]
	s_waitcnt lgkmcnt(0)
	v_mfma_f32_32x32x16_bf16 v[48:63], v[132:135], v[108:111], v[48:63]
	global_load_dwordx4 v[96:99], v66, s[38:39]
	global_load_dwordx4 v[108:111], v[68:69], off offset:3200
	s_waitcnt vmcnt(7)
	ds_write_b128 v73, v[88:91] offset:46080
	s_waitcnt vmcnt(6)
	ds_write_b128 v73, v[100:103] offset:9216
	v_mfma_f32_32x32x16_bf16 v[32:47], v[132:135], v[112:115], v[32:47]
	v_mfma_f32_32x32x16_bf16 v[16:31], v[132:135], v[120:123], v[16:31]
	ds_read_b128 v[88:91], v76 offset:64
	ds_read_b128 v[100:103], v76 offset:4672
	ds_read_b128 v[112:115], v76 offset:9280
	ds_read_b128 v[120:123], v76 offset:13888
	ds_read_b128 v[124:127], v75 offset:64
	v_mfma_f32_32x32x16_bf16 v[0:15], v[132:135], v[128:131], v[0:15]
	s_waitcnt lgkmcnt(0)
	v_mfma_f32_32x32x16_bf16 v[48:63], v[124:127], v[88:91], v[48:63]
	global_load_dwordx4 v[88:91], v66, s[40:41]
	s_waitcnt vmcnt(6)
	ds_write_b128 v73, v[84:87] offset:55296
	v_mfma_f32_32x32x16_bf16 v[32:47], v[124:127], v[100:103], v[32:47]
	v_mfma_f32_32x32x16_bf16 v[16:31], v[124:127], v[112:115], v[16:31]
	ds_read_b128 v[84:87], v76 offset:96
	ds_read_b128 v[100:103], v76 offset:4704
	ds_read_b128 v[112:115], v76 offset:9312
	ds_read_b128 v[128:131], v76 offset:13920
	ds_read_b128 v[132:135], v75 offset:96
	v_mfma_f32_32x32x16_bf16 v[0:15], v[124:127], v[120:123], v[0:15]
	s_waitcnt lgkmcnt(0)
	v_mfma_f32_32x32x16_bf16 v[48:63], v[132:135], v[84:87], v[48:63]
	global_load_dwordx4 v[84:87], v66, s[44:45]
	s_waitcnt vmcnt(6)
	ds_write_b128 v73, v[92:95] offset:64512
	v_mfma_f32_32x32x16_bf16 v[32:47], v[132:135], v[100:103], v[32:47]
	v_mfma_f32_32x32x16_bf16 v[16:31], v[132:135], v[112:115], v[16:31]
	v_mfma_f32_32x32x16_bf16 v[0:15], v[132:135], v[128:131], v[0:15]
	s_waitcnt lgkmcnt(0)
	s_barrier
	ds_read_b128 v[92:95], v72 offset:36864
	ds_read_b128 v[100:103], v74
	ds_read_b128 v[112:115], v74 offset:4608
	s_waitcnt lgkmcnt(1)
	v_mfma_f32_32x32x16_bf16 v[48:63], v[92:95], v[100:103], v[48:63]
	s_waitcnt lgkmcnt(0)
	v_mfma_f32_32x32x16_bf16 v[32:47], v[92:95], v[112:115], v[32:47]
	global_load_dwordx4 v[100:103], v66, s[4:5] offset:3328
	global_load_dwordx4 v[112:115], v66, s[34:35] offset:3328
	ds_read_b128 v[120:123], v74 offset:9216
	ds_read_b128 v[124:127], v74 offset:13824
	s_waitcnt vmcnt(7)
	ds_write_b128 v77, v[104:107]
	s_waitcnt vmcnt(6)
	ds_write_b128 v78, v[116:119]
	s_waitcnt lgkmcnt(3)
	v_mfma_f32_32x32x16_bf16 v[16:31], v[92:95], v[120:123], v[16:31]
	ds_read_b128 v[104:107], v74 offset:32
	ds_read_b128 v[116:119], v74 offset:4640
	ds_read_b128 v[120:123], v74 offset:9248
	ds_read_b128 v[128:131], v74 offset:13856
	ds_read_b128 v[132:135], v72 offset:36896
	s_waitcnt lgkmcnt(7)
	v_mfma_f32_32x32x16_bf16 v[0:15], v[92:95], v[124:127], v[0:15]
	s_waitcnt lgkmcnt(0)
	v_mfma_f32_32x32x16_bf16 v[48:63], v[132:135], v[104:107], v[48:63]
	global_load_dwordx4 v[92:95], v66, s[46:47]
	global_load_dwordx4 v[104:107], v[68:69], off offset:3328
	s_waitcnt vmcnt(7)
	ds_write_b128 v79, v[96:99]
	s_waitcnt vmcnt(6)
	ds_write_b128 v80, v[108:111]
	v_mfma_f32_32x32x16_bf16 v[32:47], v[132:135], v[116:119], v[32:47]
	v_mfma_f32_32x32x16_bf16 v[16:31], v[132:135], v[120:123], v[16:31]
	ds_read_b128 v[96:99], v74 offset:64
	ds_read_b128 v[108:111], v74 offset:4672
	ds_read_b128 v[116:119], v74 offset:9280
	ds_read_b128 v[120:123], v74 offset:13888
	ds_read_b128 v[124:127], v72 offset:36928
	v_mfma_f32_32x32x16_bf16 v[0:15], v[132:135], v[128:131], v[0:15]
	s_waitcnt lgkmcnt(0)
	v_mfma_f32_32x32x16_bf16 v[48:63], v[124:127], v[96:99], v[48:63]
	global_load_dwordx4 v[96:99], v66, s[50:51]
	s_waitcnt vmcnt(6)
	ds_write_b128 v81, v[88:91]
	v_mfma_f32_32x32x16_bf16 v[32:47], v[124:127], v[108:111], v[32:47]
	v_mfma_f32_32x32x16_bf16 v[16:31], v[124:127], v[116:119], v[16:31]
	ds_read_b128 v[88:91], v74 offset:96
	ds_read_b128 v[108:111], v74 offset:4704
	ds_read_b128 v[116:119], v74 offset:9312
	ds_read_b128 v[128:131], v74 offset:13920
	ds_read_b128 v[132:135], v72 offset:36960
	v_mfma_f32_32x32x16_bf16 v[0:15], v[124:127], v[120:123], v[0:15]
	s_waitcnt lgkmcnt(0)
	v_mfma_f32_32x32x16_bf16 v[48:63], v[132:135], v[88:91], v[48:63]
	global_load_dwordx4 v[88:91], v66, s[70:71]
	s_waitcnt vmcnt(6)
	ds_write_b128 v82, v[84:87]
	v_mfma_f32_32x32x16_bf16 v[32:47], v[132:135], v[108:111], v[32:47]
	v_mfma_f32_32x32x16_bf16 v[16:31], v[132:135], v[116:119], v[16:31]
	v_mfma_f32_32x32x16_bf16 v[0:15], v[132:135], v[128:131], v[0:15]
	s_waitcnt lgkmcnt(0)
	s_barrier
; #define H_MMA(F) { _Pragma("unroll") for (int mb = 0; mb < 4; ++mb) acc[mb] = __builtin_amdgcn_mfma_f32_32x32x16_bf16(F[4], F[mb], acc[mb], 0, 0, 0); }
; DI void gemm_half_rowbf16(const bf16_t* __restrict__ A, int lda, const bf16_t* __restrict__ Bt, int ldb, int K, int m0, int n0, char* smem, bf16_t* __restrict__ Out, int ldo) {
;     ...
;   const int nk = K / 64;
;   H_LOADA(0, 0); H_LOADA(1, 0); H_LOADB(0, 0); H_LOADB(1, 0); H_LOADB(2, 0); H_LOADB(3, 0);
;   H_STOREA(0, 0); H_STOREA(0, 1); H_STOREB(0, 0); H_STOREB(0, 1); H_STOREB(0, 2); H_STOREB(0, 3);
;   if (nk > 1) { H_LOADA(0, 1); H_LOADA(1, 1); H_LOADB(0, 1); H_LOADB(1, 1); H_LOADB(2, 1); H_LOADB(3, 1); }
;   for (int kt = 0; kt < nk; ++kt) {
;     const int st = kt & 1;
;     __syncthreads();
;     bf16x8 f0[5], f1[5];
;     H_FRAGS(f0, st, 0);
;     H_PART(0, st, kt); H_FRAGS(f1, st, 1); H_MMA(f0); __builtin_amdgcn_sched_barrier(0);
;     H_PART(1, st, kt); H_FRAGS(f0, st, 2); H_MMA(f1); __builtin_amdgcn_sched_barrier(0);
;     H_PART(2, st, kt); H_FRAGS(f1, st, 3); H_MMA(f0); __builtin_amdgcn_sched_barrier(0);
;     H_PART(3, st, kt); H_MMA(f1); __builtin_amdgcn_sched_barrier(0);
;   }
	ds_read_b128 v[84:87], v75
	ds_read_b128 v[108:111], v76
	ds_read_b128 v[116:119], v76 offset:4608
	s_waitcnt lgkmcnt(1)
	v_mfma_f32_32x32x16_bf16 v[48:63], v[84:87], v[108:111], v[48:63]
	s_waitcnt lgkmcnt(0)
	v_mfma_f32_32x32x16_bf16 v[32:47], v[84:87], v[116:119], v[32:47]
	global_load_dwordx4 v[108:111], v66, s[4:5] offset:3456
	global_load_dwordx4 v[116:119], v66, s[34:35] offset:3456
	ds_read_b128 v[120:123], v76 offset:9216
	ds_read_b128 v[124:127], v76 offset:13824
	s_waitcnt vmcnt(7)
	ds_write_b128 v73, v[100:103] offset:36864
	s_waitcnt vmcnt(6)
	ds_write_b128 v73, v[112:115]
	s_waitcnt lgkmcnt(3)
	v_mfma_f32_32x32x16_bf16 v[16:31], v[84:87], v[120:123], v[16:31]
	ds_read_b128 v[100:103], v76 offset:32
	ds_read_b128 v[112:115], v76 offset:4640
	ds_read_b128 v[120:123], v76 offset:9248
	ds_read_b128 v[128:131], v76 offset:13856
	ds_read_b128 v[132:135], v75 offset:32
	s_waitcnt lgkmcnt(7)
	v_mfma_f32_32x32x16_bf16 v[0:15], v[84:87], v[124:127], v[0:15]
	s_waitcnt lgkmcnt(0)
	v_mfma_f32_32x32x16_bf16 v[48:63], v[132:135], v[100:103], v[48:63]
	global_load_dwordx4 v[84:87], v66, s[74:75]
	global_load_dwordx4 v[100:103], v[68:69], off offset:3456
	s_waitcnt vmcnt(7)
	ds_write_b128 v73, v[92:95] offset:46080
	s_waitcnt vmcnt(6)
	ds_write_b128 v73, v[104:107] offset:9216
	v_mfma_f32_32x32x16_bf16 v[32:47], v[132:135], v[112:115], v[32:47]
	v_mfma_f32_32x32x16_bf16 v[16:31], v[132:135], v[120:123], v[16:31]
	ds_read_b128 v[92:95], v76 offset:64
	ds_read_b128 v[104:107], v76 offset:4672
	ds_read_b128 v[112:115], v76 offset:9280
	ds_read_b128 v[120:123], v76 offset:13888
	ds_read_b128 v[124:127], v75 offset:64
	v_mfma_f32_32x32x16_bf16 v[0:15], v[132:135], v[128:131], v[0:15]
	s_waitcnt lgkmcnt(0)
	v_mfma_f32_32x32x16_bf16 v[48:63], v[124:127], v[92:95], v[48:63]
	global_load_dwordx4 v[92:95], v66, s[24:25]
	s_waitcnt vmcnt(6)
	ds_write_b128 v73, v[96:99] offset:55296
	v_mfma_f32_32x32x16_bf16 v[32:47], v[124:127], v[104:107], v[32:47]
	v_mfma_f32_32x32x16_bf16 v[16:31], v[124:127], v[112:115], v[16:31]
	ds_read_b128 v[96:99], v76 offset:96
	ds_read_b128 v[104:107], v76 offset:4704
	ds_read_b128 v[112:115], v76 offset:9312
	ds_read_b128 v[128:131], v76 offset:13920
	ds_read_b128 v[132:135], v75 offset:96
	v_mfma_f32_32x32x16_bf16 v[0:15], v[124:127], v[120:123], v[0:15]
	s_waitcnt lgkmcnt(0)
	v_mfma_f32_32x32x16_bf16 v[48:63], v[132:135], v[96:99], v[48:63]
	global_load_dwordx4 v[96:99], v66, s[2:3]
	s_waitcnt vmcnt(6)
	ds_write_b128 v73, v[88:91] offset:64512
	v_mfma_f32_32x32x16_bf16 v[32:47], v[132:135], v[104:107], v[32:47]
	v_mfma_f32_32x32x16_bf16 v[16:31], v[132:135], v[112:115], v[16:31]
	v_mfma_f32_32x32x16_bf16 v[0:15], v[132:135], v[128:131], v[0:15]
	s_waitcnt lgkmcnt(0)
	s_barrier
	ds_read_b128 v[88:91], v72 offset:36864
	ds_read_b128 v[104:107], v74
	ds_read_b128 v[112:115], v74 offset:4608
	s_waitcnt lgkmcnt(1)
	v_mfma_f32_32x32x16_bf16 v[48:63], v[88:91], v[104:107], v[48:63]
	s_waitcnt lgkmcnt(0)
	v_mfma_f32_32x32x16_bf16 v[32:47], v[88:91], v[112:115], v[32:47]
	global_load_dwordx4 v[104:107], v66, s[4:5] offset:3584
	global_load_dwordx4 v[112:115], v66, s[34:35] offset:3584
	ds_read_b128 v[120:123], v74 offset:9216
	ds_read_b128 v[124:127], v74 offset:13824
	s_waitcnt vmcnt(7)
	ds_write_b128 v77, v[108:111]
	s_waitcnt vmcnt(6)
	ds_write_b128 v78, v[116:119]
	s_waitcnt lgkmcnt(3)
	v_mfma_f32_32x32x16_bf16 v[16:31], v[88:91], v[120:123], v[16:31]
	ds_read_b128 v[108:111], v74 offset:32
	ds_read_b128 v[116:119], v74 offset:4640
	ds_read_b128 v[120:123], v74 offset:9248
	ds_read_b128 v[128:131], v74 offset:13856
	ds_read_b128 v[132:135], v72 offset:36896
	s_waitcnt lgkmcnt(7)
	v_mfma_f32_32x32x16_bf16 v[0:15], v[88:91], v[124:127], v[0:15]
	s_waitcnt lgkmcnt(0)
	v_mfma_f32_32x32x16_bf16 v[48:63], v[132:135], v[108:111], v[48:63]
	global_load_dwordx4 v[88:91], v66, s[56:57]
	global_load_dwordx4 v[108:111], v[68:69], off offset:3584
	s_waitcnt vmcnt(7)
	ds_write_b128 v79, v[84:87]
	s_waitcnt vmcnt(6)
	ds_write_b128 v80, v[100:103]
	v_mfma_f32_32x32x16_bf16 v[32:47], v[132:135], v[116:119], v[32:47]
	v_mfma_f32_32x32x16_bf16 v[16:31], v[132:135], v[120:123], v[16:31]
	ds_read_b128 v[84:87], v74 offset:64
	ds_read_b128 v[100:103], v74 offset:4672
	ds_read_b128 v[116:119], v74 offset:9280
	ds_read_b128 v[120:123], v74 offset:13888
	ds_read_b128 v[124:127], v72 offset:36928
	v_mfma_f32_32x32x16_bf16 v[0:15], v[132:135], v[128:131], v[0:15]
	s_waitcnt lgkmcnt(0)
	v_mfma_f32_32x32x16_bf16 v[48:63], v[124:127], v[84:87], v[48:63]
	global_load_dwordx4 v[84:87], v66, s[58:59]
	s_waitcnt vmcnt(6)
	ds_write_b128 v81, v[92:95]
	v_mfma_f32_32x32x16_bf16 v[32:47], v[124:127], v[100:103], v[32:47]
	v_mfma_f32_32x32x16_bf16 v[16:31], v[124:127], v[116:119], v[16:31]
	ds_read_b128 v[92:95], v74 offset:96
	ds_read_b128 v[100:103], v74 offset:4704
	ds_read_b128 v[116:119], v74 offset:9312
	ds_read_b128 v[128:131], v74 offset:13920
	ds_read_b128 v[132:135], v72 offset:36960
	v_mfma_f32_32x32x16_bf16 v[0:15], v[124:127], v[120:123], v[0:15]
	s_waitcnt lgkmcnt(0)
	v_mfma_f32_32x32x16_bf16 v[48:63], v[132:135], v[92:95], v[48:63]
	global_load_dwordx4 v[92:95], v66, s[60:61]
	s_waitcnt vmcnt(6)
	ds_write_b128 v82, v[96:99]
	v_mfma_f32_32x32x16_bf16 v[32:47], v[132:135], v[100:103], v[32:47]
	v_mfma_f32_32x32x16_bf16 v[16:31], v[132:135], v[116:119], v[16:31]
	v_mfma_f32_32x32x16_bf16 v[0:15], v[132:135], v[128:131], v[0:15]
	s_waitcnt lgkmcnt(0)
	s_barrier
; #define H_MMA(F) { _Pragma("unroll") for (int mb = 0; mb < 4; ++mb) acc[mb] = __builtin_amdgcn_mfma_f32_32x32x16_bf16(F[4], F[mb], acc[mb], 0, 0, 0); }
; DI void gemm_half_rowbf16(const bf16_t* __restrict__ A, int lda, const bf16_t* __restrict__ Bt, int ldb, int K, int m0, int n0, char* smem, bf16_t* __restrict__ Out, int ldo) {
;     ...
;   const int nk = K / 64;
;   H_LOADA(0, 0); H_LOADA(1, 0); H_LOADB(0, 0); H_LOADB(1, 0); H_LOADB(2, 0); H_LOADB(3, 0);
;   H_STOREA(0, 0); H_STOREA(0, 1); H_STOREB(0, 0); H_STOREB(0, 1); H_STOREB(0, 2); H_STOREB(0, 3);
;   if (nk > 1) { H_LOADA(0, 1); H_LOADA(1, 1); H_LOADB(0, 1); H_LOADB(1, 1); H_LOADB(2, 1); H_LOADB(3, 1); }
;   for (int kt = 0; kt < nk; ++kt) {
;     const int st = kt & 1;
;     __syncthreads();
;     bf16x8 f0[5], f1[5];
;     H_FRAGS(f0, st, 0);
;     H_PART(0, st, kt); H_FRAGS(f1, st, 1); H_MMA(f0); __builtin_amdgcn_sched_barrier(0);
;     H_PART(1, st, kt); H_FRAGS(f0, st, 2); H_MMA(f1); __builtin_amdgcn_sched_barrier(0);
;     H_PART(2, st, kt); H_FRAGS(f1, st, 3); H_MMA(f0); __builtin_amdgcn_sched_barrier(0);
;     H_PART(3, st, kt); H_MMA(f1); __builtin_amdgcn_sched_barrier(0);
;   }
	ds_read_b128 v[96:99], v75
	ds_read_b128 v[100:103], v76
	ds_read_b128 v[116:119], v76 offset:4608
	s_waitcnt lgkmcnt(1)
	v_mfma_f32_32x32x16_bf16 v[48:63], v[96:99], v[100:103], v[48:63]
	s_waitcnt lgkmcnt(0)
	v_mfma_f32_32x32x16_bf16 v[32:47], v[96:99], v[116:119], v[32:47]
	global_load_dwordx4 v[100:103], v66, s[4:5] offset:3712
	global_load_dwordx4 v[116:119], v66, s[34:35] offset:3712
	ds_read_b128 v[120:123], v76 offset:9216
	ds_read_b128 v[124:127], v76 offset:13824
	s_waitcnt vmcnt(7)
	ds_write_b128 v73, v[104:107] offset:36864
	s_waitcnt vmcnt(6)
	ds_write_b128 v73, v[112:115]
	s_waitcnt lgkmcnt(3)
	v_mfma_f32_32x32x16_bf16 v[16:31], v[96:99], v[120:123], v[16:31]
	ds_read_b128 v[104:107], v76 offset:32
	ds_read_b128 v[112:115], v76 offset:4640
	ds_read_b128 v[120:123], v76 offset:9248
	ds_read_b128 v[128:131], v76 offset:13856
	ds_read_b128 v[132:135], v75 offset:32
	s_waitcnt lgkmcnt(7)
	v_mfma_f32_32x32x16_bf16 v[0:15], v[96:99], v[124:127], v[0:15]
	s_waitcnt lgkmcnt(0)
	v_mfma_f32_32x32x16_bf16 v[48:63], v[132:135], v[104:107], v[48:63]
	global_load_dwordx4 v[96:99], v66, s[62:63]
	global_load_dwordx4 v[104:107], v[68:69], off offset:3712
	s_waitcnt vmcnt(7)
	ds_write_b128 v73, v[88:91] offset:46080
	s_waitcnt vmcnt(6)
	ds_write_b128 v73, v[108:111] offset:9216
	v_mfma_f32_32x32x16_bf16 v[32:47], v[132:135], v[112:115], v[32:47]
	v_mfma_f32_32x32x16_bf16 v[16:31], v[132:135], v[120:123], v[16:31]
	ds_read_b128 v[88:91], v76 offset:64
	ds_read_b128 v[108:111], v76 offset:4672
	ds_read_b128 v[112:115], v76 offset:9280
	ds_read_b128 v[120:123], v76 offset:13888
	ds_read_b128 v[124:127], v75 offset:64
	v_mfma_f32_32x32x16_bf16 v[0:15], v[132:135], v[128:131], v[0:15]
	s_waitcnt lgkmcnt(0)
	v_mfma_f32_32x32x16_bf16 v[48:63], v[124:127], v[88:91], v[48:63]
	global_load_dwordx4 v[88:91], v66, s[64:65]
	s_waitcnt vmcnt(6)
	ds_write_b128 v73, v[84:87] offset:55296
	v_mfma_f32_32x32x16_bf16 v[32:47], v[124:127], v[108:111], v[32:47]
	v_mfma_f32_32x32x16_bf16 v[16:31], v[124:127], v[112:115], v[16:31]
	ds_read_b128 v[84:87], v76 offset:96
	ds_read_b128 v[108:111], v76 offset:4704
	ds_read_b128 v[112:115], v76 offset:9312
	ds_read_b128 v[128:131], v76 offset:13920
	ds_read_b128 v[132:135], v75 offset:96
	v_mfma_f32_32x32x16_bf16 v[0:15], v[124:127], v[120:123], v[0:15]
	s_waitcnt lgkmcnt(0)
	v_mfma_f32_32x32x16_bf16 v[48:63], v[132:135], v[84:87], v[48:63]
	global_load_dwordx4 v[84:87], v66, s[6:7]
	s_waitcnt vmcnt(6)
	ds_write_b128 v73, v[92:95] offset:64512
	v_mfma_f32_32x32x16_bf16 v[32:47], v[132:135], v[108:111], v[32:47]
	v_mfma_f32_32x32x16_bf16 v[16:31], v[132:135], v[112:115], v[16:31]
	v_mfma_f32_32x32x16_bf16 v[0:15], v[132:135], v[128:131], v[0:15]
	s_waitcnt lgkmcnt(0)
	s_barrier
	ds_read_b128 v[92:95], v72 offset:36864
	ds_read_b128 v[108:111], v74
	ds_read_b128 v[112:115], v74 offset:4608
	s_waitcnt lgkmcnt(1)
	v_mfma_f32_32x32x16_bf16 v[48:63], v[92:95], v[108:111], v[48:63]
	s_waitcnt lgkmcnt(0)
	v_mfma_f32_32x32x16_bf16 v[32:47], v[92:95], v[112:115], v[32:47]
	global_load_dwordx4 v[108:111], v66, s[4:5] offset:3840
	global_load_dwordx4 v[112:115], v66, s[34:35] offset:3840
	ds_read_b128 v[120:123], v74 offset:9216
	ds_read_b128 v[124:127], v74 offset:13824
	s_waitcnt vmcnt(7)
	ds_write_b128 v77, v[100:103]
	s_waitcnt vmcnt(6)
	ds_write_b128 v78, v[116:119]
	s_waitcnt lgkmcnt(3)
	v_mfma_f32_32x32x16_bf16 v[16:31], v[92:95], v[120:123], v[16:31]
	ds_read_b128 v[100:103], v74 offset:32
	ds_read_b128 v[116:119], v74 offset:4640
	ds_read_b128 v[120:123], v74 offset:9248
	ds_read_b128 v[128:131], v74 offset:13856
	ds_read_b128 v[132:135], v72 offset:36896
	s_waitcnt lgkmcnt(7)
	v_mfma_f32_32x32x16_bf16 v[0:15], v[92:95], v[124:127], v[0:15]
	s_waitcnt lgkmcnt(0)
	v_mfma_f32_32x32x16_bf16 v[48:63], v[132:135], v[100:103], v[48:63]
	global_load_dwordx4 v[92:95], v66, s[8:9]
	global_load_dwordx4 v[100:103], v[68:69], off offset:3840
	s_waitcnt vmcnt(7)
	ds_write_b128 v79, v[96:99]
	s_waitcnt vmcnt(6)
	ds_write_b128 v80, v[104:107]
	v_mfma_f32_32x32x16_bf16 v[32:47], v[132:135], v[116:119], v[32:47]
	v_mfma_f32_32x32x16_bf16 v[16:31], v[132:135], v[120:123], v[16:31]
	ds_read_b128 v[96:99], v74 offset:64
	ds_read_b128 v[104:107], v74 offset:4672
	ds_read_b128 v[116:119], v74 offset:9280
	ds_read_b128 v[120:123], v74 offset:13888
	ds_read_b128 v[124:127], v72 offset:36928
	v_mfma_f32_32x32x16_bf16 v[0:15], v[132:135], v[128:131], v[0:15]
	s_waitcnt lgkmcnt(0)
	v_mfma_f32_32x32x16_bf16 v[48:63], v[124:127], v[96:99], v[48:63]
	global_load_dwordx4 v[96:99], v66, s[10:11]
	s_waitcnt vmcnt(6)
	ds_write_b128 v81, v[88:91]
	v_mfma_f32_32x32x16_bf16 v[32:47], v[124:127], v[104:107], v[32:47]
	v_mfma_f32_32x32x16_bf16 v[16:31], v[124:127], v[116:119], v[16:31]
	ds_read_b128 v[88:91], v74 offset:96
	ds_read_b128 v[104:107], v74 offset:4704
	ds_read_b128 v[116:119], v74 offset:9312
	ds_read_b128 v[128:131], v74 offset:13920
	ds_read_b128 v[132:135], v72 offset:36960
	v_mfma_f32_32x32x16_bf16 v[0:15], v[124:127], v[120:123], v[0:15]
	s_waitcnt lgkmcnt(0)
	v_mfma_f32_32x32x16_bf16 v[48:63], v[132:135], v[88:91], v[48:63]
	global_load_dwordx4 v[88:91], v66, s[12:13]
	s_waitcnt vmcnt(6)
	ds_write_b128 v82, v[84:87]
	v_mfma_f32_32x32x16_bf16 v[32:47], v[132:135], v[104:107], v[32:47]
	v_mfma_f32_32x32x16_bf16 v[16:31], v[132:135], v[116:119], v[16:31]
	v_mfma_f32_32x32x16_bf16 v[0:15], v[132:135], v[128:131], v[0:15]
	s_waitcnt lgkmcnt(0)
	s_barrier
; #define H_MMA(F) { _Pragma("unroll") for (int mb = 0; mb < 4; ++mb) acc[mb] = __builtin_amdgcn_mfma_f32_32x32x16_bf16(F[4], F[mb], acc[mb], 0, 0, 0); }
; DI void gemm_half_rowbf16(const bf16_t* __restrict__ A, int lda, const bf16_t* __restrict__ Bt, int ldb, int K, int m0, int n0, char* smem, bf16_t* __restrict__ Out, int ldo) {
;     ...
;   const int nk = K / 64;
;   H_LOADA(0, 0); H_LOADA(1, 0); H_LOADB(0, 0); H_LOADB(1, 0); H_LOADB(2, 0); H_LOADB(3, 0);
;   H_STOREA(0, 0); H_STOREA(0, 1); H_STOREB(0, 0); H_STOREB(0, 1); H_STOREB(0, 2); H_STOREB(0, 3);
;   if (nk > 1) { H_LOADA(0, 1); H_LOADA(1, 1); H_LOADB(0, 1); H_LOADB(1, 1); H_LOADB(2, 1); H_LOADB(3, 1); }
;   for (int kt = 0; kt < nk; ++kt) {
;     const int st = kt & 1;
;     __syncthreads();
;     bf16x8 f0[5], f1[5];
;     H_FRAGS(f0, st, 0);
;     H_PART(0, st, kt); H_FRAGS(f1, st, 1); H_MMA(f0); __builtin_amdgcn_sched_barrier(0);
;     H_PART(1, st, kt); H_FRAGS(f0, st, 2); H_MMA(f1); __builtin_amdgcn_sched_barrier(0);
;     H_PART(2, st, kt); H_FRAGS(f1, st, 3); H_MMA(f0); __builtin_amdgcn_sched_barrier(0);
;     H_PART(3, st, kt); H_MMA(f1); __builtin_amdgcn_sched_barrier(0);
;   }
	ds_read_b128 v[84:87], v75
	ds_read_b128 v[104:107], v76
	ds_read_b128 v[116:119], v76 offset:4608
	s_waitcnt lgkmcnt(1)
	v_mfma_f32_32x32x16_bf16 v[48:63], v[84:87], v[104:107], v[48:63]
	s_waitcnt lgkmcnt(0)
	v_mfma_f32_32x32x16_bf16 v[32:47], v[84:87], v[116:119], v[32:47]
	global_load_dwordx4 v[104:107], v66, s[4:5] offset:3968
	global_load_dwordx4 v[116:119], v66, s[34:35] offset:3968
	ds_read_b128 v[120:123], v76 offset:9216
	ds_read_b128 v[124:127], v76 offset:13824
	s_waitcnt vmcnt(7)
	ds_write_b128 v73, v[108:111] offset:36864
	s_waitcnt vmcnt(6)
	ds_write_b128 v73, v[112:115]
	s_waitcnt lgkmcnt(3)
	v_mfma_f32_32x32x16_bf16 v[16:31], v[84:87], v[120:123], v[16:31]
	ds_read_b128 v[108:111], v76 offset:32
	ds_read_b128 v[112:115], v76 offset:4640
	ds_read_b128 v[120:123], v76 offset:9248
	ds_read_b128 v[128:131], v76 offset:13856
	ds_read_b128 v[132:135], v75 offset:32
	s_waitcnt lgkmcnt(7)
	v_mfma_f32_32x32x16_bf16 v[0:15], v[84:87], v[124:127], v[0:15]
	s_waitcnt lgkmcnt(0)
	v_mfma_f32_32x32x16_bf16 v[48:63], v[132:135], v[108:111], v[48:63]
	global_load_dwordx4 v[84:87], v66, s[14:15]
	global_load_dwordx4 v[108:111], v[68:69], off offset:3968
	s_waitcnt vmcnt(7)
	ds_write_b128 v73, v[92:95] offset:46080
	s_waitcnt vmcnt(6)
	ds_write_b128 v73, v[100:103] offset:9216
	v_mfma_f32_32x32x16_bf16 v[32:47], v[132:135], v[112:115], v[32:47]
	v_mfma_f32_32x32x16_bf16 v[16:31], v[132:135], v[120:123], v[16:31]
	ds_read_b128 v[92:95], v76 offset:64
	ds_read_b128 v[100:103], v76 offset:4672
	ds_read_b128 v[112:115], v76 offset:9280
	ds_read_b128 v[120:123], v76 offset:13888
	ds_read_b128 v[124:127], v75 offset:64
	v_mfma_f32_32x32x16_bf16 v[0:15], v[132:135], v[128:131], v[0:15]
	s_waitcnt lgkmcnt(0)
	v_mfma_f32_32x32x16_bf16 v[48:63], v[124:127], v[92:95], v[48:63]
	global_load_dwordx4 v[92:95], v66, s[26:27]
	s_waitcnt vmcnt(6)
	ds_write_b128 v73, v[96:99] offset:55296
	v_mfma_f32_32x32x16_bf16 v[32:47], v[124:127], v[100:103], v[32:47]
	v_mfma_f32_32x32x16_bf16 v[16:31], v[124:127], v[112:115], v[16:31]
	ds_read_b128 v[96:99], v76 offset:96
	ds_read_b128 v[100:103], v76 offset:4704
	ds_read_b128 v[112:115], v76 offset:9312
	ds_read_b128 v[128:131], v76 offset:13920
	ds_read_b128 v[132:135], v75 offset:96
	v_mfma_f32_32x32x16_bf16 v[0:15], v[124:127], v[120:123], v[0:15]
	s_waitcnt lgkmcnt(0)
	v_mfma_f32_32x32x16_bf16 v[48:63], v[132:135], v[96:99], v[48:63]
	global_load_dwordx4 v[96:99], v66, s[28:29]
	s_waitcnt vmcnt(6)
	ds_write_b128 v73, v[88:91] offset:64512
	v_mfma_f32_32x32x16_bf16 v[32:47], v[132:135], v[100:103], v[32:47]
	v_mfma_f32_32x32x16_bf16 v[16:31], v[132:135], v[112:115], v[16:31]
	v_mfma_f32_32x32x16_bf16 v[0:15], v[132:135], v[128:131], v[0:15]
	s_waitcnt lgkmcnt(0)
	s_barrier
	ds_read_b128 v[88:91], v72 offset:36864
	ds_read_b128 v[100:103], v74
	ds_read_b128 v[112:115], v74 offset:4608
	s_waitcnt lgkmcnt(1)
	v_mfma_f32_32x32x16_bf16 v[48:63], v[88:91], v[100:103], v[48:63]
	s_waitcnt lgkmcnt(0)
	v_mfma_f32_32x32x16_bf16 v[32:47], v[88:91], v[112:115], v[32:47]
	ds_read_b128 v[100:103], v74 offset:9216
	ds_read_b128 v[112:115], v74 offset:13824
	s_waitcnt vmcnt(5)
	ds_write_b128 v77, v[104:107]
	s_waitcnt vmcnt(4)
	ds_write_b128 v78, v[116:119]
	s_waitcnt lgkmcnt(3)
	v_mfma_f32_32x32x16_bf16 v[16:31], v[88:91], v[100:103], v[16:31]
	ds_read_b128 v[100:103], v74 offset:32
	ds_read_b128 v[104:107], v74 offset:4640
	ds_read_b128 v[116:119], v74 offset:9248
	ds_read_b128 v[120:123], v74 offset:13856
	ds_read_b128 v[124:127], v72 offset:36896
	s_waitcnt lgkmcnt(7)
	v_mfma_f32_32x32x16_bf16 v[0:15], v[88:91], v[112:115], v[0:15]
	s_waitcnt vmcnt(3)
	ds_write_b128 v79, v[84:87]
	s_waitcnt vmcnt(2)
	ds_write_b128 v80, v[108:111]
	s_waitcnt lgkmcnt(2)
	v_mfma_f32_32x32x16_bf16 v[48:63], v[124:127], v[100:103], v[48:63]
	v_mfma_f32_32x32x16_bf16 v[32:47], v[124:127], v[104:107], v[32:47]
	ds_read_b128 v[84:87], v74 offset:64
	ds_read_b128 v[88:91], v74 offset:4672
	ds_read_b128 v[100:103], v74 offset:9280
	ds_read_b128 v[104:107], v74 offset:13888
	ds_read_b128 v[108:111], v72 offset:36928
	v_mfma_f32_32x32x16_bf16 v[16:31], v[124:127], v[116:119], v[16:31]
	v_mfma_f32_32x32x16_bf16 v[0:15], v[124:127], v[120:123], v[0:15]
	s_waitcnt vmcnt(1)
	ds_write_b128 v81, v[92:95]
	s_waitcnt lgkmcnt(1)
	v_mfma_f32_32x32x16_bf16 v[48:63], v[108:111], v[84:87], v[48:63]
	v_mfma_f32_32x32x16_bf16 v[32:47], v[108:111], v[88:91], v[32:47]
	v_mfma_f32_32x32x16_bf16 v[16:31], v[108:111], v[100:103], v[16:31]
	ds_read_b128 v[78:81], v74 offset:96
	ds_read_b128 v[84:87], v74 offset:4704
	ds_read_b128 v[88:91], v74 offset:9312
	ds_read_b128 v[92:95], v74 offset:13920
	ds_read_b128 v[100:103], v72 offset:36960
	v_mfma_f32_32x32x16_bf16 v[0:15], v[108:111], v[104:107], v[0:15]
	s_waitcnt lgkmcnt(0)
	v_mfma_f32_32x32x16_bf16 v[48:63], v[100:103], v[78:81], v[48:63]
	s_waitcnt vmcnt(0)
	ds_write_b128 v82, v[96:99]
	v_mfma_f32_32x32x16_bf16 v[32:47], v[100:103], v[84:87], v[32:47]
	v_mfma_f32_32x32x16_bf16 v[16:31], v[100:103], v[88:91], v[16:31]
	v_mfma_f32_32x32x16_bf16 v[0:15], v[100:103], v[92:95], v[0:15]
	s_waitcnt lgkmcnt(0)
	s_barrier
;   DI bf16_t* wt_in0() const { return (bf16_t*)(ws + OFF_WT_IN0); }
;   DI bf16_t* h() const { return (bf16_t*)(ws + OFF_H); }
;   DI bf16_t* z() const { return (bf16_t*)(ws + OFF_Z); }
; #define H_MMA(F) { _Pragma("unroll") for (int mb = 0; mb < 4; ++mb) acc[mb] = __builtin_amdgcn_mfma_f32_32x32x16_bf16(F[4], F[mb], acc[mb], 0, 0, 0); }
; DI void gemm_half_rowbf16(const bf16_t* __restrict__ A, int lda, const bf16_t* __restrict__ Bt, int ldb, int K, int m0, int n0, char* smem, bf16_t* __restrict__ Out, int ldo) {
;     ...
;     H_PART(0, st, kt); H_FRAGS(f1, st, 1); H_MMA(f0); __builtin_amdgcn_sched_barrier(0);
;     H_PART(1, st, kt); H_FRAGS(f0, st, 2); H_MMA(f1); __builtin_amdgcn_sched_barrier(0);
;     H_PART(2, st, kt); H_FRAGS(f1, st, 3); H_MMA(f0); __builtin_amdgcn_sched_barrier(0);
;     H_PART(3, st, kt); H_MMA(f1); __builtin_amdgcn_sched_barrier(0);
;   }
;   __syncthreads();
;     ...
; #pragma unroll
;   for (int mb = 0; mb < 4; ++mb) {
;     const size_t tok = m0 + 32 * mb + l32;
; #pragma unroll
;     for (int j = 0; j < 4; ++j) {
;       const int n = n0 + 32 * w + 8 * j + 4 * g;
;       u32x2 wv; wv.x = pk_bf16(acc[mb][4 * j], acc[mb][4 * j + 1]); wv.y = pk_bf16(acc[mb][4 * j + 2], acc[mb][4 * j + 3]);
;       *(u32x2*)(Out + tok * ldo + n) = wv;
;     }
;   }
; DI void phase_gemm_in0(const Params& p, char* smem) {
;     ...
;   for (int t = blockIdx.x; t < 128; t += gridDim.x) gemm_half_rowbf16(p.h(), D, p.wt_in0(), D, D, t * 128, 16 * 256, smem, p.z(), LDZ0);
	ds_read_b128 v[78:81], v75
	ds_read_b128 v[82:85], v76
	ds_read_b128 v[86:89], v76 offset:32
	ds_read_b128 v[90:93], v75 offset:32
	s_waitcnt lgkmcnt(2)
	v_mfma_f32_32x32x16_bf16 v[48:63], v[78:81], v[82:85], v[48:63]
	ds_read_b128 v[82:85], v76 offset:4608
	ds_read_b128 v[94:97], v76 offset:4640
	s_waitcnt lgkmcnt(1)
	v_mfma_f32_32x32x16_bf16 v[32:47], v[78:81], v[82:85], v[32:47]
	ds_read_b128 v[82:85], v76 offset:9216
	ds_read_b128 v[98:101], v76 offset:9248
	s_waitcnt lgkmcnt(1)
	v_mfma_f32_32x32x16_bf16 v[16:31], v[78:81], v[82:85], v[16:31]
	ds_read_b128 v[82:85], v76 offset:13824
	ds_read_b128 v[102:105], v76 offset:13856
	s_waitcnt lgkmcnt(1)
	v_mfma_f32_32x32x16_bf16 v[0:15], v[78:81], v[82:85], v[0:15]
	v_mfma_f32_32x32x16_bf16 v[48:63], v[90:93], v[86:89], v[48:63]
	v_mfma_f32_32x32x16_bf16 v[32:47], v[90:93], v[94:97], v[32:47]
	v_mfma_f32_32x32x16_bf16 v[16:31], v[90:93], v[98:101], v[16:31]
	ds_read_b128 v[78:81], v76 offset:64
	ds_read_b128 v[82:85], v76 offset:4672
	ds_read_b128 v[86:89], v76 offset:9280
	ds_read_b128 v[94:97], v76 offset:13888
	ds_read_b128 v[98:101], v75 offset:64
	s_waitcnt lgkmcnt(5)
	v_mfma_f32_32x32x16_bf16 v[0:15], v[90:93], v[102:105], v[0:15]
	s_waitcnt lgkmcnt(0)
	v_mfma_f32_32x32x16_bf16 v[48:63], v[98:101], v[78:81], v[48:63]
	v_mfma_f32_32x32x16_bf16 v[32:47], v[98:101], v[82:85], v[32:47]
	v_mfma_f32_32x32x16_bf16 v[16:31], v[98:101], v[86:89], v[16:31]
	ds_read_b128 v[78:81], v76 offset:96
	ds_read_b128 v[82:85], v76 offset:4704
	ds_read_b128 v[86:89], v76 offset:9312
	ds_read_b128 v[90:93], v76 offset:13920
	ds_read_b128 v[72:75], v75 offset:96
	v_mfma_f32_32x32x16_bf16 v[0:15], v[98:101], v[94:97], v[0:15]
	s_waitcnt lgkmcnt(0)
	v_mfma_f32_32x32x16_bf16 v[48:63], v[72:75], v[78:81], v[48:63]
	v_mfma_f32_32x32x16_bf16 v[32:47], v[72:75], v[82:85], v[32:47]
	v_mfma_f32_32x32x16_bf16 v[16:31], v[72:75], v[86:89], v[16:31]
	v_mfma_f32_32x32x16_bf16 v[0:15], v[72:75], v[90:93], v[0:15]
	s_addk_i32 s31, 0x1000
	v_lshl_or_b32 v68, v70, 2, s31
	v_add_u32_e32 v66, s30, v71
	v_ashrrev_i32_e32 v69, 31, v68
	v_mad_i64_i32 v[70:71], s[34:35], v66, s43, v[64:65]
	s_nop 3
	v_cvt_pk_bf16_f32 v48, v48, v49
	v_cvt_pk_bf16_f32 v49, v50, v51
	v_lshlrev_b64 v[50:51], 1, v[68:69]
	v_lshl_add_u64 v[72:73], v[70:71], 0, v[50:51]
	s_barrier
	global_store_dwordx2 v[72:73], v[48:49], off
	v_or_b32_e32 v48, 8, v68
	v_ashrrev_i32_e32 v49, 31, v48
	v_lshlrev_b64 v[48:49], 1, v[48:49]
	v_cvt_pk_bf16_f32 v52, v52, v53
	v_cvt_pk_bf16_f32 v53, v54, v55
	v_lshl_add_u64 v[54:55], v[70:71], 0, v[48:49]
	global_store_dwordx2 v[54:55], v[52:53], off
	v_or_b32_e32 v52, 16, v68
	v_ashrrev_i32_e32 v53, 31, v52
	v_lshlrev_b64 v[52:53], 1, v[52:53]
	v_cvt_pk_bf16_f32 v54, v56, v57
	v_cvt_pk_bf16_f32 v55, v58, v59
	v_lshl_add_u64 v[56:57], v[70:71], 0, v[52:53]
	global_store_dwordx2 v[56:57], v[54:55], off
	v_or_b32_e32 v54, 24, v68
	v_ashrrev_i32_e32 v55, 31, v54
	v_lshlrev_b64 v[54:55], 1, v[54:55]
	v_cvt_pk_bf16_f32 v56, v60, v61
	v_cvt_pk_bf16_f32 v57, v62, v63
	v_lshl_add_u64 v[58:59], v[70:71], 0, v[54:55]
	global_store_dwordx2 v[58:59], v[56:57], off
	v_add_u32_e32 v56, 32, v66
	v_mad_i64_i32 v[56:57], s[34:35], v56, s43, v[64:65]
	v_cvt_pk_bf16_f32 v32, v32, v33
	v_cvt_pk_bf16_f32 v33, v34, v35
	v_lshl_add_u64 v[34:35], v[56:57], 0, v[50:51]
	global_store_dwordx2 v[34:35], v[32:33], off
	v_cvt_pk_bf16_f32 v32, v36, v37
	v_cvt_pk_bf16_f32 v33, v38, v39
	v_lshl_add_u64 v[34:35], v[56:57], 0, v[48:49]
	global_store_dwordx2 v[34:35], v[32:33], off
	v_cvt_pk_bf16_f32 v32, v40, v41
	v_cvt_pk_bf16_f32 v33, v42, v43
	v_lshl_add_u64 v[34:35], v[56:57], 0, v[52:53]
	global_store_dwordx2 v[34:35], v[32:33], off
	v_cvt_pk_bf16_f32 v32, v44, v45
	v_cvt_pk_bf16_f32 v33, v46, v47
	v_lshl_add_u64 v[34:35], v[56:57], 0, v[54:55]
	global_store_dwordx2 v[34:35], v[32:33], off
	v_add_u32_e32 v32, 64, v66
	v_mad_i64_i32 v[32:33], s[34:35], v32, s43, v[64:65]
	v_cvt_pk_bf16_f32 v16, v16, v17
	v_cvt_pk_bf16_f32 v17, v18, v19
	v_lshl_add_u64 v[18:19], v[32:33], 0, v[50:51]
	global_store_dwordx2 v[18:19], v[16:17], off
	v_cvt_pk_bf16_f32 v16, v20, v21
	v_cvt_pk_bf16_f32 v17, v22, v23
	v_lshl_add_u64 v[18:19], v[32:33], 0, v[48:49]
	global_store_dwordx2 v[18:19], v[16:17], off
	v_cvt_pk_bf16_f32 v16, v24, v25
	v_cvt_pk_bf16_f32 v17, v26, v27
	v_lshl_add_u64 v[18:19], v[32:33], 0, v[52:53]
	global_store_dwordx2 v[18:19], v[16:17], off
	v_cvt_pk_bf16_f32 v16, v28, v29
	v_cvt_pk_bf16_f32 v17, v30, v31
	v_lshl_add_u64 v[18:19], v[32:33], 0, v[54:55]
	global_store_dwordx2 v[18:19], v[16:17], off
	v_add_u32_e32 v16, 0x60, v66
	v_mad_i64_i32 v[16:17], s[34:35], v16, s43, v[64:65]
	v_cvt_pk_bf16_f32 v0, v0, v1
	v_cvt_pk_bf16_f32 v1, v2, v3
	v_lshl_add_u64 v[2:3], v[16:17], 0, v[50:51]
	global_store_dwordx2 v[2:3], v[0:1], off
	v_cvt_pk_bf16_f32 v0, v4, v5
	v_cvt_pk_bf16_f32 v1, v6, v7
	v_lshl_add_u64 v[2:3], v[16:17], 0, v[48:49]
	v_readlane_b32 s31, v250, 49
	global_store_dwordx2 v[2:3], v[0:1], off
	v_cvt_pk_bf16_f32 v0, v8, v9
	v_cvt_pk_bf16_f32 v1, v10, v11
	v_lshl_add_u64 v[2:3], v[16:17], 0, v[52:53]
	s_add_i32 s48, s48, s96
	s_add_i32 s30, s30, s31
	global_store_dwordx2 v[2:3], v[0:1], off
	v_cvt_pk_bf16_f32 v0, v12, v13
	v_cvt_pk_bf16_f32 v1, v14, v15
	v_lshl_add_u64 v[2:3], v[16:17], 0, v[54:55]
	s_cmpk_lt_i32 s48, 0x80
	global_store_dwordx2 v[2:3], v[0:1], off
	s_cbranch_scc1 .LBB0_131
	v_readlane_b32 s68, v252, 41
	v_readlane_b32 s94, v252, 57
	v_readlane_b32 s69, v252, 42
	v_readlane_b32 s70, v252, 43
	v_readlane_b32 s71, v252, 44
	v_readlane_b32 s72, v252, 45
	v_readlane_b32 s73, v252, 46
	v_readlane_b32 s76, v252, 49
	v_readlane_b32 s77, v252, 50
	v_readlane_b32 s78, v252, 51
	v_readlane_b32 s79, v252, 52
	v_readlane_b32 s82, v252, 55
	v_readlane_b32 s83, v252, 56
	v_readlane_b32 s95, v252, 58
	v_readlane_b32 s84, v250, 50
	v_readlane_b32 s74, v252, 47
	v_readlane_b32 s75, v252, 48
	v_readlane_b32 s80, v252, 53
	v_readlane_b32 s81, v252, 54
	v_readlane_b32 s85, v250, 51
	s_branch .LBB0_133
.Lprep2_tramp:
	s_mov_b32 s100, s96
	s_addk_i32 s84, 0x2a0
	s_movk_i32 s96, 0x80
	s_movk_i32 s99, 0xfcf
	s_mov_b32 s101, 1
	v_lshlrev_b32_e32 v2, 2, v206
	s_branch .Lprep_entry
.Lprep2_ret:
	s_addk_i32 s84, 0xfd60
	s_mov_b32 s96, s100
	s_mov_b32 s101, 0
